# L slot: LDS-DMA issues interleaved with ds_read_b128 (1 DMA : 3 reads) in merged P8/P9 loops
# speedup vs baseline: 1.0774x; 1.0048x over previous
; #define PG8_STAGE(bufoff, gbase, voff) do { _Pragma("unroll") for (int _i = 0; _i < 2; ++_i) \
;         __builtin_amdgcn_global_load_lds((const unsigned*)((const char*)(gbase) + (voff)[_i]), (PG8_LAS unsigned*)(lds + (bufoff) + ldsw + _i * 8192), 16, 0, 0); } while (0)
; #define PG8_LDA(dst, b, h) do { _Pragma("unroll") for (int m = 0; m < 4; ++m) _Pragma("unroll") for (int k = 0; k < 2; ++k) dst[m][k] = *(const PG8_LAS bf16x8*)(lds + PG8_SA(b, h) + aoff + m * 2048 + k * 1024); } while (0)
; #define PG8_LDB(dst, b, h) do { _Pragma("unroll") for (int n = 0; n < 2; ++n) _Pragma("unroll") for (int k = 0; k < 2; ++k) dst[n][k] = *(const PG8_LAS bf16x8*)(lds + PG8_SB(b, h) + boff + n * 2048 + k * 1024); } while (0)
; #define PG8_MMA(ai, bj, At, Bt) do { __builtin_amdgcn_s_setprio(1); _Pragma("unroll") for (int m = 0; m < 4; ++m) _Pragma("unroll") for (int n = 0; n < 2; ++n) _Pragma("unroll") for (int k = 0; k < 2; ++k) \
;         acc[ai][bj][m][n] = __builtin_amdgcn_mfma_f32_16x16x32_bf16(Bt[n][k], At[m][k], acc[ai][bj][m][n], 0, 0, 0); __builtin_amdgcn_s_setprio(0); } while (0)
; #define PG8_WAIT_V(n) asm volatile("s_waitcnt vmcnt(" #n ")" ::: "memory")
; #define PG8_WAIT_L(n) asm volatile("s_waitcnt lgkmcnt(" #n ")" ::: "memory")
; #define PG8_BAR __builtin_amdgcn_s_barrier()
; #define PG8_SCHED __builtin_amdgcn_sched_barrier(0)
; template <class Epi, class Sched, bool ALIGN_EPI>
; __device__ __forceinline__ void gemm_phase(PG8_LAS unsigned char* lds, const Gemm g, const Sched& S, const Epi& E) {
;     ...
;             PG8_LDB(B0, 0, 0); PG8_LDB(B1, 0, 1); PG8_SCHED; PG8_LDA(At, 0, 0); PG8_STAGE(PG8_SA(1, 1), a1 + hstepA, voffA);
;             PG8_WAIT_V(8); PG8_WAIT_L(0); PG8_BAR; PG8_MMA(0, 0, At, B0); PG8_MMA(0, 1, At, B1); PG8_BAR; PG8_SCHED;
;             PG8_LDA(At, 0, 1); PG8_STAGE(PG8_SB(0, 0), b2, voffB); PG8_STAGE(PG8_SB(0, 1), b2 + hstepB, voffB); PG8_STAGE(PG8_SA(0, 0), a2, voffA);
;             PG8_WAIT_V(8); PG8_WAIT_L(0); PG8_BAR; PG8_MMA(1, 0, At, B0); PG8_MMA(1, 1, At, B1); PG8_BAR; PG8_SCHED;
.Lp8k_A_loop:
	s_add_i32 m0, s2, 0x18000
	s_nop 0
	global_load_lds_dwordx4 v134, s[28:29]
	ds_read_b128 v[190:193], v155 offset:0
	ds_read_b128 v[194:197], v155 offset:1024
	ds_read_b128 v[198:201], v155 offset:2048
	s_add_i32 m0, s2, 0x1a000
	s_nop 0
	global_load_lds_dwordx4 v130, s[28:29]
	ds_read_b128 v[202:205], v155 offset:3072
	ds_read_b128 v[206:209], v155 offset:4096
	ds_read_b128 v[210:213], v155 offset:5120
	s_add_u32 s30, s28, 0x20000
	s_addc_u32 s31, s29, 0
	s_add_i32 m0, s2, 0x19000
	s_nop 0
	global_load_lds_dwordx4 v134, s[30:31]
	ds_read_b128 v[214:217], v155 offset:6144
	ds_read_b128 v[218:221], v155 offset:7168
	ds_read_b128 v[156:159], v153 offset:0
	s_add_i32 m0, s2, 0x1b000
	s_nop 0
	global_load_lds_dwordx4 v130, s[30:31]
	ds_read_b128 v[160:163], v153 offset:1024
	ds_read_b128 v[164:167], v153 offset:2048
	ds_read_b128 v[168:171], v153 offset:3072
	s_add_u32 s30, s28, 0x80000
	s_addc_u32 s31, s29, 0
	s_add_i32 m0, s2, 0x1c000
	s_nop 0
	global_load_lds_dwordx4 v134, s[30:31]
	ds_read_b128 v[174:177], v153 offset:16384
	ds_read_b128 v[178:181], v153 offset:17408
	ds_read_b128 v[182:185], v153 offset:18432
	s_add_i32 m0, s2, 0x1e000
	s_nop 0
	global_load_lds_dwordx4 v130, s[30:31]
	ds_read_b128 v[186:189], v153 offset:19456
	ds_read_b128 v[222:225], v155 offset:16384
	ds_read_b128 v[226:229], v155 offset:17408
	s_add_u32 s30, s28, 0xa0000
	s_addc_u32 s31, s29, 0
	s_add_i32 m0, s2, 0x1d000
	s_nop 0
	global_load_lds_dwordx4 v134, s[30:31]
	ds_read_b128 v[230:233], v155 offset:18432
	ds_read_b128 v[234:237], v155 offset:19456
	ds_read_b128 v[238:241], v155 offset:20480
	s_add_i32 m0, s2, 0x1f000
	s_nop 0
	global_load_lds_dwordx4 v130, s[30:31]
	ds_read_b128 v[242:245], v155 offset:21504
	ds_read_b128 v[246:249], v155 offset:22528
	ds_read_b128 v[250:253], v155 offset:23552
	s_add_u32 s28, s28, 0x80
	s_addc_u32 s29, s29, 0
	s_waitcnt vmcnt(8) lgkmcnt(0)
	s_barrier
	s_setprio 1
	v_mfma_f32_16x16x32_bf16 v[126:129], v[156:159], v[190:193], v[126:129]
	v_mfma_f32_16x16x32_bf16 v[126:129], v[160:163], v[194:197], v[126:129]
	v_mfma_f32_16x16x32_bf16 v[122:125], v[168:171], v[194:197], v[122:125]
	v_mfma_f32_16x16x32_bf16 v[122:125], v[164:167], v[190:193], v[122:125]
	v_mfma_f32_16x16x32_bf16 v[118:121], v[174:177], v[190:193], v[118:121]
	v_mfma_f32_16x16x32_bf16 v[118:121], v[178:181], v[194:197], v[118:121]
	v_mfma_f32_16x16x32_bf16 v[114:117], v[186:189], v[194:197], v[114:117]
	v_mfma_f32_16x16x32_bf16 v[114:117], v[182:185], v[190:193], v[114:117]
	v_mfma_f32_16x16x32_bf16 v[98:101], v[182:185], v[198:201], v[98:101]
	v_mfma_f32_16x16x32_bf16 v[98:101], v[186:189], v[202:205], v[98:101]
	v_mfma_f32_16x16x32_bf16 v[102:105], v[178:181], v[202:205], v[102:105]
	v_mfma_f32_16x16x32_bf16 v[102:105], v[174:177], v[198:201], v[102:105]
	v_mfma_f32_16x16x32_bf16 v[106:109], v[164:167], v[198:201], v[106:109]
	v_mfma_f32_16x16x32_bf16 v[106:109], v[168:171], v[202:205], v[106:109]
	v_mfma_f32_16x16x32_bf16 v[110:113], v[160:163], v[202:205], v[110:113]
	v_mfma_f32_16x16x32_bf16 v[110:113], v[156:159], v[198:201], v[110:113]
	v_mfma_f32_16x16x32_bf16 v[94:97], v[156:159], v[206:209], v[94:97]
	v_mfma_f32_16x16x32_bf16 v[94:97], v[160:163], v[210:213], v[94:97]
	v_mfma_f32_16x16x32_bf16 v[90:93], v[168:171], v[210:213], v[90:93]
	v_mfma_f32_16x16x32_bf16 v[90:93], v[164:167], v[206:209], v[90:93]
	v_mfma_f32_16x16x32_bf16 v[86:89], v[174:177], v[206:209], v[86:89]
	v_mfma_f32_16x16x32_bf16 v[86:89], v[178:181], v[210:213], v[86:89]
	v_mfma_f32_16x16x32_bf16 v[82:85], v[186:189], v[210:213], v[82:85]
	v_mfma_f32_16x16x32_bf16 v[82:85], v[182:185], v[206:209], v[82:85]
	v_mfma_f32_16x16x32_bf16 v[66:69], v[182:185], v[214:217], v[66:69]
	v_mfma_f32_16x16x32_bf16 v[66:69], v[186:189], v[218:221], v[66:69]
	v_mfma_f32_16x16x32_bf16 v[70:73], v[178:181], v[218:221], v[70:73]
	v_mfma_f32_16x16x32_bf16 v[70:73], v[174:177], v[214:217], v[70:73]
	v_mfma_f32_16x16x32_bf16 v[74:77], v[164:167], v[214:217], v[74:77]
	v_mfma_f32_16x16x32_bf16 v[74:77], v[168:171], v[218:221], v[74:77]
	v_mfma_f32_16x16x32_bf16 v[78:81], v[160:163], v[218:221], v[78:81]
	v_mfma_f32_16x16x32_bf16 v[78:81], v[156:159], v[214:217], v[78:81]
	v_mfma_f32_16x16x32_bf16 v[62:65], v[156:159], v[222:225], v[62:65]
	v_mfma_f32_16x16x32_bf16 v[62:65], v[160:163], v[226:229], v[62:65]
	v_mfma_f32_16x16x32_bf16 v[58:61], v[168:171], v[226:229], v[58:61]
	v_mfma_f32_16x16x32_bf16 v[58:61], v[164:167], v[222:225], v[58:61]
	v_mfma_f32_16x16x32_bf16 v[54:57], v[174:177], v[222:225], v[54:57]
	v_mfma_f32_16x16x32_bf16 v[54:57], v[178:181], v[226:229], v[54:57]
	v_mfma_f32_16x16x32_bf16 v[50:53], v[186:189], v[226:229], v[50:53]
	v_mfma_f32_16x16x32_bf16 v[50:53], v[182:185], v[222:225], v[50:53]
	v_mfma_f32_16x16x32_bf16 v[34:37], v[182:185], v[230:233], v[34:37]
	v_mfma_f32_16x16x32_bf16 v[34:37], v[186:189], v[234:237], v[34:37]
	v_mfma_f32_16x16x32_bf16 v[38:41], v[178:181], v[234:237], v[38:41]
	v_mfma_f32_16x16x32_bf16 v[38:41], v[174:177], v[230:233], v[38:41]
	v_mfma_f32_16x16x32_bf16 v[42:45], v[164:167], v[230:233], v[42:45]
	v_mfma_f32_16x16x32_bf16 v[42:45], v[168:171], v[234:237], v[42:45]
	v_mfma_f32_16x16x32_bf16 v[46:49], v[160:163], v[234:237], v[46:49]
	v_mfma_f32_16x16x32_bf16 v[46:49], v[156:159], v[230:233], v[46:49]
	v_mfma_f32_16x16x32_bf16 v[30:33], v[156:159], v[238:241], v[30:33]
	v_mfma_f32_16x16x32_bf16 v[30:33], v[160:163], v[242:245], v[30:33]
	v_mfma_f32_16x16x32_bf16 v[26:29], v[168:171], v[242:245], v[26:29]
	v_mfma_f32_16x16x32_bf16 v[26:29], v[164:167], v[238:241], v[26:29]
	v_mfma_f32_16x16x32_bf16 v[22:25], v[174:177], v[238:241], v[22:25]
	v_mfma_f32_16x16x32_bf16 v[22:25], v[178:181], v[242:245], v[22:25]
	v_mfma_f32_16x16x32_bf16 v[18:21], v[186:189], v[242:245], v[18:21]
	v_mfma_f32_16x16x32_bf16 v[18:21], v[182:185], v[238:241], v[18:21]
	v_mfma_f32_16x16x32_bf16 v[2:5], v[182:185], v[246:249], v[2:5]
	v_mfma_f32_16x16x32_bf16 v[2:5], v[186:189], v[250:253], v[2:5]
	v_mfma_f32_16x16x32_bf16 v[6:9], v[178:181], v[250:253], v[6:9]
	v_mfma_f32_16x16x32_bf16 v[6:9], v[174:177], v[246:249], v[6:9]
	v_mfma_f32_16x16x32_bf16 v[10:13], v[164:167], v[246:249], v[10:13]
	v_mfma_f32_16x16x32_bf16 v[10:13], v[168:171], v[250:253], v[10:13]
	v_mfma_f32_16x16x32_bf16 v[14:17], v[160:163], v[250:253], v[14:17]
	v_mfma_f32_16x16x32_bf16 v[14:17], v[156:159], v[246:249], v[14:17]
	s_setprio 0
	s_waitcnt vmcnt(0)
	s_barrier
; #define PG8_STAGE(bufoff, gbase, voff) do { _Pragma("unroll") for (int _i = 0; _i < 2; ++_i) \
;         __builtin_amdgcn_global_load_lds((const unsigned*)((const char*)(gbase) + (voff)[_i]), (PG8_LAS unsigned*)(lds + (bufoff) + ldsw + _i * 8192), 16, 0, 0); } while (0)
; #define PG8_LDA(dst, b, h) do { _Pragma("unroll") for (int m = 0; m < 4; ++m) _Pragma("unroll") for (int k = 0; k < 2; ++k) dst[m][k] = *(const PG8_LAS bf16x8*)(lds + PG8_SA(b, h) + aoff + m * 2048 + k * 1024); } while (0)
; #define PG8_LDB(dst, b, h) do { _Pragma("unroll") for (int n = 0; n < 2; ++n) _Pragma("unroll") for (int k = 0; k < 2; ++k) dst[n][k] = *(const PG8_LAS bf16x8*)(lds + PG8_SB(b, h) + boff + n * 2048 + k * 1024); } while (0)
; #define PG8_MMA(ai, bj, At, Bt) do { __builtin_amdgcn_s_setprio(1); _Pragma("unroll") for (int m = 0; m < 4; ++m) _Pragma("unroll") for (int n = 0; n < 2; ++n) _Pragma("unroll") for (int k = 0; k < 2; ++k) \
;         acc[ai][bj][m][n] = __builtin_amdgcn_mfma_f32_16x16x32_bf16(Bt[n][k], At[m][k], acc[ai][bj][m][n], 0, 0, 0); __builtin_amdgcn_s_setprio(0); } while (0)
; #define PG8_WAIT_V(n) asm volatile("s_waitcnt vmcnt(" #n ")" ::: "memory")
; #define PG8_WAIT_L(n) asm volatile("s_waitcnt lgkmcnt(" #n ")" ::: "memory")
; #define PG8_BAR __builtin_amdgcn_s_barrier()
; #define PG8_SCHED __builtin_amdgcn_sched_barrier(0)
; template <class Epi, class Sched, bool ALIGN_EPI>
; __device__ __forceinline__ void gemm_phase(PG8_LAS unsigned char* lds, const Gemm g, const Sched& S, const Epi& E) {
;     ...
;             PG8_LDB(B0, 1, 0); PG8_LDB(B1, 1, 1); PG8_SCHED; PG8_LDA(At, 1, 0); PG8_STAGE(PG8_SA(0, 1), a2 + hstepA, voffA);
;             PG8_WAIT_V(8); PG8_WAIT_L(0); PG8_BAR; PG8_MMA(0, 0, At, B0); PG8_MMA(0, 1, At, B1); PG8_BAR; PG8_SCHED;
;             PG8_LDA(At, 1, 1); PG8_STAGE(PG8_SB(1, 0), b3, voffB); PG8_STAGE(PG8_SB(1, 1), b3 + hstepB, voffB); PG8_STAGE(PG8_SA(1, 0), a3, voffA);
;             PG8_WAIT_V(8); PG8_WAIT_L(0); PG8_BAR; PG8_MMA(1, 0, At, B0); PG8_MMA(1, 1, At, B1); PG8_BAR; PG8_SCHED;
;         }
	s_cmp_eq_u32 s49, 15
	s_cselect_b32 s28, s50, s28
	s_cselect_b32 s29, s51, s29
	s_add_i32 m0, s2, 0x10000
	s_nop 0
	global_load_lds_dwordx4 v134, s[28:29]
	ds_read_b128 v[190:193], v155 offset:32768
	ds_read_b128 v[194:197], v155 offset:33792
	ds_read_b128 v[198:201], v155 offset:34816
	s_add_i32 m0, s2, 0x12000
	s_nop 0
	global_load_lds_dwordx4 v130, s[28:29]
	ds_read_b128 v[202:205], v155 offset:35840
	ds_read_b128 v[206:209], v155 offset:36864
	ds_read_b128 v[210:213], v155 offset:37888
	s_add_u32 s30, s28, 0x20000
	s_addc_u32 s31, s29, 0
	s_add_i32 m0, s2, 0x11000
	s_nop 0
	global_load_lds_dwordx4 v134, s[30:31]
	ds_read_b128 v[214:217], v155 offset:38912
	ds_read_b128 v[218:221], v155 offset:39936
	ds_read_b128 v[156:159], v153 offset:32768
	s_add_i32 m0, s2, 0x13000
	s_nop 0
	global_load_lds_dwordx4 v130, s[30:31]
	ds_read_b128 v[160:163], v153 offset:33792
	ds_read_b128 v[164:167], v153 offset:34816
	ds_read_b128 v[168:171], v153 offset:35840
	s_add_u32 s30, s28, 0x80000
	s_addc_u32 s31, s29, 0
	s_add_i32 m0, s2, 0x14000
	s_nop 0
	global_load_lds_dwordx4 v134, s[30:31]
	ds_read_b128 v[174:177], v153 offset:49152
	ds_read_b128 v[178:181], v153 offset:50176
	ds_read_b128 v[182:185], v153 offset:51200
	s_add_i32 m0, s2, 0x16000
	s_nop 0
	global_load_lds_dwordx4 v130, s[30:31]
	ds_read_b128 v[186:189], v153 offset:52224
	ds_read_b128 v[222:225], v155 offset:49152
	ds_read_b128 v[226:229], v155 offset:50176
	s_add_u32 s30, s28, 0xa0000
	s_addc_u32 s31, s29, 0
	s_add_i32 m0, s2, 0x15000
	s_nop 0
	global_load_lds_dwordx4 v134, s[30:31]
	ds_read_b128 v[230:233], v155 offset:51200
	ds_read_b128 v[234:237], v155 offset:52224
	ds_read_b128 v[238:241], v155 offset:53248
	s_add_i32 m0, s2, 0x17000
	s_nop 0
	global_load_lds_dwordx4 v130, s[30:31]
	ds_read_b128 v[242:245], v155 offset:54272
	ds_read_b128 v[246:249], v155 offset:55296
	ds_read_b128 v[250:253], v155 offset:56320
	s_add_u32 s28, s28, 0x80
	s_addc_u32 s29, s29, 0
	s_waitcnt vmcnt(8) lgkmcnt(0)
	s_barrier
	s_setprio 1
	v_mfma_f32_16x16x32_bf16 v[126:129], v[156:159], v[190:193], v[126:129]
	v_mfma_f32_16x16x32_bf16 v[126:129], v[160:163], v[194:197], v[126:129]
	v_mfma_f32_16x16x32_bf16 v[122:125], v[168:171], v[194:197], v[122:125]
	v_mfma_f32_16x16x32_bf16 v[122:125], v[164:167], v[190:193], v[122:125]
	v_mfma_f32_16x16x32_bf16 v[118:121], v[174:177], v[190:193], v[118:121]
	v_mfma_f32_16x16x32_bf16 v[118:121], v[178:181], v[194:197], v[118:121]
	v_mfma_f32_16x16x32_bf16 v[114:117], v[186:189], v[194:197], v[114:117]
	v_mfma_f32_16x16x32_bf16 v[114:117], v[182:185], v[190:193], v[114:117]
	v_mfma_f32_16x16x32_bf16 v[98:101], v[182:185], v[198:201], v[98:101]
	v_mfma_f32_16x16x32_bf16 v[98:101], v[186:189], v[202:205], v[98:101]
	v_mfma_f32_16x16x32_bf16 v[102:105], v[178:181], v[202:205], v[102:105]
	v_mfma_f32_16x16x32_bf16 v[102:105], v[174:177], v[198:201], v[102:105]
	v_mfma_f32_16x16x32_bf16 v[106:109], v[164:167], v[198:201], v[106:109]
	v_mfma_f32_16x16x32_bf16 v[106:109], v[168:171], v[202:205], v[106:109]
	v_mfma_f32_16x16x32_bf16 v[110:113], v[160:163], v[202:205], v[110:113]
	v_mfma_f32_16x16x32_bf16 v[110:113], v[156:159], v[198:201], v[110:113]
	v_mfma_f32_16x16x32_bf16 v[94:97], v[156:159], v[206:209], v[94:97]
	v_mfma_f32_16x16x32_bf16 v[94:97], v[160:163], v[210:213], v[94:97]
	v_mfma_f32_16x16x32_bf16 v[90:93], v[168:171], v[210:213], v[90:93]
	v_mfma_f32_16x16x32_bf16 v[90:93], v[164:167], v[206:209], v[90:93]
	v_mfma_f32_16x16x32_bf16 v[86:89], v[174:177], v[206:209], v[86:89]
	v_mfma_f32_16x16x32_bf16 v[86:89], v[178:181], v[210:213], v[86:89]
	v_mfma_f32_16x16x32_bf16 v[82:85], v[186:189], v[210:213], v[82:85]
	v_mfma_f32_16x16x32_bf16 v[82:85], v[182:185], v[206:209], v[82:85]
	v_mfma_f32_16x16x32_bf16 v[66:69], v[182:185], v[214:217], v[66:69]
	v_mfma_f32_16x16x32_bf16 v[66:69], v[186:189], v[218:221], v[66:69]
	v_mfma_f32_16x16x32_bf16 v[70:73], v[178:181], v[218:221], v[70:73]
	v_mfma_f32_16x16x32_bf16 v[70:73], v[174:177], v[214:217], v[70:73]
	v_mfma_f32_16x16x32_bf16 v[74:77], v[164:167], v[214:217], v[74:77]
	v_mfma_f32_16x16x32_bf16 v[74:77], v[168:171], v[218:221], v[74:77]
	v_mfma_f32_16x16x32_bf16 v[78:81], v[160:163], v[218:221], v[78:81]
	v_mfma_f32_16x16x32_bf16 v[78:81], v[156:159], v[214:217], v[78:81]
	v_mfma_f32_16x16x32_bf16 v[62:65], v[156:159], v[222:225], v[62:65]
	v_mfma_f32_16x16x32_bf16 v[62:65], v[160:163], v[226:229], v[62:65]
	v_mfma_f32_16x16x32_bf16 v[58:61], v[168:171], v[226:229], v[58:61]
	v_mfma_f32_16x16x32_bf16 v[58:61], v[164:167], v[222:225], v[58:61]
	v_mfma_f32_16x16x32_bf16 v[54:57], v[174:177], v[222:225], v[54:57]
	v_mfma_f32_16x16x32_bf16 v[54:57], v[178:181], v[226:229], v[54:57]
	v_mfma_f32_16x16x32_bf16 v[50:53], v[186:189], v[226:229], v[50:53]
	v_mfma_f32_16x16x32_bf16 v[50:53], v[182:185], v[222:225], v[50:53]
	v_mfma_f32_16x16x32_bf16 v[34:37], v[182:185], v[230:233], v[34:37]
	v_mfma_f32_16x16x32_bf16 v[34:37], v[186:189], v[234:237], v[34:37]
	v_mfma_f32_16x16x32_bf16 v[38:41], v[178:181], v[234:237], v[38:41]
	v_mfma_f32_16x16x32_bf16 v[38:41], v[174:177], v[230:233], v[38:41]
	v_mfma_f32_16x16x32_bf16 v[42:45], v[164:167], v[230:233], v[42:45]
	v_mfma_f32_16x16x32_bf16 v[42:45], v[168:171], v[234:237], v[42:45]
	v_mfma_f32_16x16x32_bf16 v[46:49], v[160:163], v[234:237], v[46:49]
	v_mfma_f32_16x16x32_bf16 v[46:49], v[156:159], v[230:233], v[46:49]
	v_mfma_f32_16x16x32_bf16 v[30:33], v[156:159], v[238:241], v[30:33]
	v_mfma_f32_16x16x32_bf16 v[30:33], v[160:163], v[242:245], v[30:33]
	v_mfma_f32_16x16x32_bf16 v[26:29], v[168:171], v[242:245], v[26:29]
	v_mfma_f32_16x16x32_bf16 v[26:29], v[164:167], v[238:241], v[26:29]
	v_mfma_f32_16x16x32_bf16 v[22:25], v[174:177], v[238:241], v[22:25]
	v_mfma_f32_16x16x32_bf16 v[22:25], v[178:181], v[242:245], v[22:25]
	v_mfma_f32_16x16x32_bf16 v[18:21], v[186:189], v[242:245], v[18:21]
	v_mfma_f32_16x16x32_bf16 v[18:21], v[182:185], v[238:241], v[18:21]
	v_mfma_f32_16x16x32_bf16 v[2:5], v[182:185], v[246:249], v[2:5]
	v_mfma_f32_16x16x32_bf16 v[2:5], v[186:189], v[250:253], v[2:5]
	v_mfma_f32_16x16x32_bf16 v[6:9], v[178:181], v[250:253], v[6:9]
	v_mfma_f32_16x16x32_bf16 v[6:9], v[174:177], v[246:249], v[6:9]
	v_mfma_f32_16x16x32_bf16 v[10:13], v[164:167], v[246:249], v[10:13]
	v_mfma_f32_16x16x32_bf16 v[10:13], v[168:171], v[250:253], v[10:13]
	v_mfma_f32_16x16x32_bf16 v[14:17], v[160:163], v[250:253], v[14:17]
	v_mfma_f32_16x16x32_bf16 v[14:17], v[156:159], v[246:249], v[14:17]
	s_setprio 0
	s_waitcnt vmcnt(0)
	s_barrier
	s_add_i32 s49, s49, 1
	s_cmp_lt_u32 s49, 16
	s_cbranch_scc1 .Lp8k_A_loop
	s_branch .Lp8k_done

; #define PG8_STAGE(bufoff, gbase, voff) do { _Pragma("unroll") for (int _i = 0; _i < 2; ++_i) \
;         __builtin_amdgcn_global_load_lds((const unsigned*)((const char*)(gbase) + (voff)[_i]), (PG8_LAS unsigned*)(lds + (bufoff) + ldsw + _i * 8192), 16, 0, 0); } while (0)
; #define PG8_LDA(dst, b, h) do { _Pragma("unroll") for (int m = 0; m < 4; ++m) _Pragma("unroll") for (int k = 0; k < 2; ++k) dst[m][k] = *(const PG8_LAS bf16x8*)(lds + PG8_SA(b, h) + aoff + m * 2048 + k * 1024); } while (0)
; #define PG8_LDB(dst, b, h) do { _Pragma("unroll") for (int n = 0; n < 2; ++n) _Pragma("unroll") for (int k = 0; k < 2; ++k) dst[n][k] = *(const PG8_LAS bf16x8*)(lds + PG8_SB(b, h) + boff + n * 2048 + k * 1024); } while (0)
; #define PG8_MMA(ai, bj, At, Bt) do { __builtin_amdgcn_s_setprio(1); _Pragma("unroll") for (int m = 0; m < 4; ++m) _Pragma("unroll") for (int n = 0; n < 2; ++n) _Pragma("unroll") for (int k = 0; k < 2; ++k) \
;         acc[ai][bj][m][n] = __builtin_amdgcn_mfma_f32_16x16x32_bf16(Bt[n][k], At[m][k], acc[ai][bj][m][n], 0, 0, 0); __builtin_amdgcn_s_setprio(0); } while (0)
; #define PG8_WAIT_V(n) asm volatile("s_waitcnt vmcnt(" #n ")" ::: "memory")
; #define PG8_WAIT_L(n) asm volatile("s_waitcnt lgkmcnt(" #n ")" ::: "memory")
; #define PG8_BAR __builtin_amdgcn_s_barrier()
; #define PG8_SCHED __builtin_amdgcn_sched_barrier(0)
; template <class Epi, class Sched, bool ALIGN_EPI>
; __device__ __forceinline__ void gemm_phase(PG8_LAS unsigned char* lds, const Gemm g, const Sched& S, const Epi& E) {
;     ...
;             PG8_LDB(B0, 0, 0); PG8_LDB(B1, 0, 1); PG8_SCHED; PG8_LDA(At, 0, 0); PG8_STAGE(PG8_SA(1, 1), a1 + hstepA, voffA);
;             PG8_WAIT_V(8); PG8_WAIT_L(0); PG8_BAR; PG8_MMA(0, 0, At, B0); PG8_MMA(0, 1, At, B1); PG8_BAR; PG8_SCHED;
;             PG8_LDA(At, 0, 1); PG8_STAGE(PG8_SB(0, 0), b2, voffB); PG8_STAGE(PG8_SB(0, 1), b2 + hstepB, voffB); PG8_STAGE(PG8_SA(0, 0), a2, voffA);
;             PG8_WAIT_V(8); PG8_WAIT_L(0); PG8_BAR; PG8_MMA(1, 0, At, B0); PG8_MMA(1, 1, At, B1); PG8_BAR; PG8_SCHED;
.Lp8k_B_loop:
	s_add_i32 m0, s2, 0xa000
	s_nop 0
	global_load_lds_dwordx4 v132, s[28:29]
	ds_read_b128 v[190:193], v155 offset:0
	ds_read_b128 v[194:197], v155 offset:1024
	ds_read_b128 v[198:201], v155 offset:2048
	s_add_u32 s30, s28, 0x20000
	s_addc_u32 s31, s29, 0
	s_add_i32 m0, s2, 0xb000
	s_nop 0
	global_load_lds_dwordx4 v132, s[30:31]
	ds_read_b128 v[202:205], v155 offset:3072
	ds_read_b128 v[206:209], v155 offset:4096
	ds_read_b128 v[210:213], v155 offset:5120
	s_add_u32 s30, s28, 0x80000
	s_addc_u32 s31, s29, 0
	s_add_i32 m0, s2, 0xe000
	s_nop 0
	global_load_lds_dwordx4 v132, s[30:31]
	ds_read_b128 v[214:217], v155 offset:6144
	ds_read_b128 v[218:221], v155 offset:7168
	ds_read_b128 v[156:159], v153 offset:0
	s_add_u32 s30, s28, 0xa0000
	s_addc_u32 s31, s29, 0
	s_add_i32 m0, s2, 0xf000
	s_nop 0
	global_load_lds_dwordx4 v132, s[30:31]
	ds_read_b128 v[160:163], v153 offset:1024
	ds_read_b128 v[164:167], v153 offset:2048
	ds_read_b128 v[168:171], v153 offset:3072
	s_add_u32 s34, s28, 0x80
	s_addc_u32 s35, s29, 0
	s_cmp_eq_u32 s49, 15
	s_cselect_b32 s34, s50, s34
	s_cselect_b32 s35, s51, s35
	s_add_i32 m0, s2, 0x0
	s_nop 0
	global_load_lds_dwordx4 v136, s[34:35]
	ds_read_b128 v[174:177], v153 offset:16384
	ds_read_b128 v[178:181], v153 offset:17408
	ds_read_b128 v[182:185], v153 offset:18432
	s_add_u32 s30, s34, 0x20000
	s_addc_u32 s31, s35, 0
	s_add_i32 m0, s2, 0x1000
	s_nop 0
	global_load_lds_dwordx4 v136, s[30:31]
	ds_read_b128 v[186:189], v153 offset:19456
	ds_read_b128 v[222:225], v155 offset:16384
	ds_read_b128 v[226:229], v155 offset:17408
	s_add_u32 s30, s34, 0x80000
	s_addc_u32 s31, s35, 0
	s_add_i32 m0, s2, 0x4000
	s_nop 0
	global_load_lds_dwordx4 v136, s[30:31]
	ds_read_b128 v[230:233], v155 offset:18432
	ds_read_b128 v[234:237], v155 offset:19456
	ds_read_b128 v[238:241], v155 offset:20480
	s_add_u32 s30, s34, 0xa0000
	s_addc_u32 s31, s35, 0
	s_add_i32 m0, s2, 0x5000
	s_nop 0
	global_load_lds_dwordx4 v136, s[30:31]
	ds_read_b128 v[242:245], v155 offset:21504
	ds_read_b128 v[246:249], v155 offset:22528
	ds_read_b128 v[250:253], v155 offset:23552
	s_add_u32 s28, s28, 0x80
	s_addc_u32 s29, s29, 0
	s_waitcnt vmcnt(8) lgkmcnt(0)
	s_barrier
	s_setprio 1
	v_mfma_f32_16x16x32_bf16 v[126:129], v[156:159], v[190:193], v[126:129]
	v_mfma_f32_16x16x32_bf16 v[126:129], v[160:163], v[194:197], v[126:129]
	v_mfma_f32_16x16x32_bf16 v[122:125], v[168:171], v[194:197], v[122:125]
	v_mfma_f32_16x16x32_bf16 v[122:125], v[164:167], v[190:193], v[122:125]
	v_mfma_f32_16x16x32_bf16 v[118:121], v[174:177], v[190:193], v[118:121]
	v_mfma_f32_16x16x32_bf16 v[118:121], v[178:181], v[194:197], v[118:121]
	v_mfma_f32_16x16x32_bf16 v[114:117], v[186:189], v[194:197], v[114:117]
	v_mfma_f32_16x16x32_bf16 v[114:117], v[182:185], v[190:193], v[114:117]
	v_mfma_f32_16x16x32_bf16 v[98:101], v[182:185], v[198:201], v[98:101]
	v_mfma_f32_16x16x32_bf16 v[98:101], v[186:189], v[202:205], v[98:101]
	v_mfma_f32_16x16x32_bf16 v[102:105], v[178:181], v[202:205], v[102:105]
	v_mfma_f32_16x16x32_bf16 v[102:105], v[174:177], v[198:201], v[102:105]
	v_mfma_f32_16x16x32_bf16 v[106:109], v[164:167], v[198:201], v[106:109]
	v_mfma_f32_16x16x32_bf16 v[106:109], v[168:171], v[202:205], v[106:109]
	v_mfma_f32_16x16x32_bf16 v[110:113], v[160:163], v[202:205], v[110:113]
	v_mfma_f32_16x16x32_bf16 v[110:113], v[156:159], v[198:201], v[110:113]
	v_mfma_f32_16x16x32_bf16 v[94:97], v[156:159], v[206:209], v[94:97]
	v_mfma_f32_16x16x32_bf16 v[94:97], v[160:163], v[210:213], v[94:97]
	v_mfma_f32_16x16x32_bf16 v[90:93], v[168:171], v[210:213], v[90:93]
	v_mfma_f32_16x16x32_bf16 v[90:93], v[164:167], v[206:209], v[90:93]
	v_mfma_f32_16x16x32_bf16 v[86:89], v[174:177], v[206:209], v[86:89]
	v_mfma_f32_16x16x32_bf16 v[86:89], v[178:181], v[210:213], v[86:89]
	v_mfma_f32_16x16x32_bf16 v[82:85], v[186:189], v[210:213], v[82:85]
	v_mfma_f32_16x16x32_bf16 v[82:85], v[182:185], v[206:209], v[82:85]
	v_mfma_f32_16x16x32_bf16 v[66:69], v[182:185], v[214:217], v[66:69]
	v_mfma_f32_16x16x32_bf16 v[66:69], v[186:189], v[218:221], v[66:69]
	v_mfma_f32_16x16x32_bf16 v[70:73], v[178:181], v[218:221], v[70:73]
	v_mfma_f32_16x16x32_bf16 v[70:73], v[174:177], v[214:217], v[70:73]
	v_mfma_f32_16x16x32_bf16 v[74:77], v[164:167], v[214:217], v[74:77]
	v_mfma_f32_16x16x32_bf16 v[74:77], v[168:171], v[218:221], v[74:77]
	v_mfma_f32_16x16x32_bf16 v[78:81], v[160:163], v[218:221], v[78:81]
	v_mfma_f32_16x16x32_bf16 v[78:81], v[156:159], v[214:217], v[78:81]
	v_mfma_f32_16x16x32_bf16 v[62:65], v[156:159], v[222:225], v[62:65]
	v_mfma_f32_16x16x32_bf16 v[62:65], v[160:163], v[226:229], v[62:65]
	v_mfma_f32_16x16x32_bf16 v[58:61], v[168:171], v[226:229], v[58:61]
	v_mfma_f32_16x16x32_bf16 v[58:61], v[164:167], v[222:225], v[58:61]
	v_mfma_f32_16x16x32_bf16 v[54:57], v[174:177], v[222:225], v[54:57]
	v_mfma_f32_16x16x32_bf16 v[54:57], v[178:181], v[226:229], v[54:57]
	v_mfma_f32_16x16x32_bf16 v[50:53], v[186:189], v[226:229], v[50:53]
	v_mfma_f32_16x16x32_bf16 v[50:53], v[182:185], v[222:225], v[50:53]
	v_mfma_f32_16x16x32_bf16 v[34:37], v[182:185], v[230:233], v[34:37]
	v_mfma_f32_16x16x32_bf16 v[34:37], v[186:189], v[234:237], v[34:37]
	v_mfma_f32_16x16x32_bf16 v[38:41], v[178:181], v[234:237], v[38:41]
	v_mfma_f32_16x16x32_bf16 v[38:41], v[174:177], v[230:233], v[38:41]
	v_mfma_f32_16x16x32_bf16 v[42:45], v[164:167], v[230:233], v[42:45]
	v_mfma_f32_16x16x32_bf16 v[42:45], v[168:171], v[234:237], v[42:45]
	v_mfma_f32_16x16x32_bf16 v[46:49], v[160:163], v[234:237], v[46:49]
	v_mfma_f32_16x16x32_bf16 v[46:49], v[156:159], v[230:233], v[46:49]
	v_mfma_f32_16x16x32_bf16 v[30:33], v[156:159], v[238:241], v[30:33]
	v_mfma_f32_16x16x32_bf16 v[30:33], v[160:163], v[242:245], v[30:33]
	v_mfma_f32_16x16x32_bf16 v[26:29], v[168:171], v[242:245], v[26:29]
	v_mfma_f32_16x16x32_bf16 v[26:29], v[164:167], v[238:241], v[26:29]
	v_mfma_f32_16x16x32_bf16 v[22:25], v[174:177], v[238:241], v[22:25]
	v_mfma_f32_16x16x32_bf16 v[22:25], v[178:181], v[242:245], v[22:25]
	v_mfma_f32_16x16x32_bf16 v[18:21], v[186:189], v[242:245], v[18:21]
	v_mfma_f32_16x16x32_bf16 v[18:21], v[182:185], v[238:241], v[18:21]
	v_mfma_f32_16x16x32_bf16 v[2:5], v[182:185], v[246:249], v[2:5]
	v_mfma_f32_16x16x32_bf16 v[2:5], v[186:189], v[250:253], v[2:5]
	v_mfma_f32_16x16x32_bf16 v[6:9], v[178:181], v[250:253], v[6:9]
	v_mfma_f32_16x16x32_bf16 v[6:9], v[174:177], v[246:249], v[6:9]
	v_mfma_f32_16x16x32_bf16 v[10:13], v[164:167], v[246:249], v[10:13]
	v_mfma_f32_16x16x32_bf16 v[10:13], v[168:171], v[250:253], v[10:13]
	v_mfma_f32_16x16x32_bf16 v[14:17], v[160:163], v[250:253], v[14:17]
	v_mfma_f32_16x16x32_bf16 v[14:17], v[156:159], v[246:249], v[14:17]
	s_setprio 0
	s_waitcnt vmcnt(0)
	s_barrier
; #define PG8_STAGE(bufoff, gbase, voff) do { _Pragma("unroll") for (int _i = 0; _i < 2; ++_i) \
;         __builtin_amdgcn_global_load_lds((const unsigned*)((const char*)(gbase) + (voff)[_i]), (PG8_LAS unsigned*)(lds + (bufoff) + ldsw + _i * 8192), 16, 0, 0); } while (0)
; #define PG8_LDA(dst, b, h) do { _Pragma("unroll") for (int m = 0; m < 4; ++m) _Pragma("unroll") for (int k = 0; k < 2; ++k) dst[m][k] = *(const PG8_LAS bf16x8*)(lds + PG8_SA(b, h) + aoff + m * 2048 + k * 1024); } while (0)
; #define PG8_LDB(dst, b, h) do { _Pragma("unroll") for (int n = 0; n < 2; ++n) _Pragma("unroll") for (int k = 0; k < 2; ++k) dst[n][k] = *(const PG8_LAS bf16x8*)(lds + PG8_SB(b, h) + boff + n * 2048 + k * 1024); } while (0)
; #define PG8_MMA(ai, bj, At, Bt) do { __builtin_amdgcn_s_setprio(1); _Pragma("unroll") for (int m = 0; m < 4; ++m) _Pragma("unroll") for (int n = 0; n < 2; ++n) _Pragma("unroll") for (int k = 0; k < 2; ++k) \
;         acc[ai][bj][m][n] = __builtin_amdgcn_mfma_f32_16x16x32_bf16(Bt[n][k], At[m][k], acc[ai][bj][m][n], 0, 0, 0); __builtin_amdgcn_s_setprio(0); } while (0)
; #define PG8_WAIT_V(n) asm volatile("s_waitcnt vmcnt(" #n ")" ::: "memory")
; #define PG8_WAIT_L(n) asm volatile("s_waitcnt lgkmcnt(" #n ")" ::: "memory")
; #define PG8_BAR __builtin_amdgcn_s_barrier()
; #define PG8_SCHED __builtin_amdgcn_sched_barrier(0)
; template <class Epi, class Sched, bool ALIGN_EPI>
; __device__ __forceinline__ void gemm_phase(PG8_LAS unsigned char* lds, const Gemm g, const Sched& S, const Epi& E) {
;     ...
;             PG8_LDB(B0, 1, 0); PG8_LDB(B1, 1, 1); PG8_SCHED; PG8_LDA(At, 1, 0); PG8_STAGE(PG8_SA(0, 1), a2 + hstepA, voffA);
;             PG8_WAIT_V(8); PG8_WAIT_L(0); PG8_BAR; PG8_MMA(0, 0, At, B0); PG8_MMA(0, 1, At, B1); PG8_BAR; PG8_SCHED;
;             PG8_LDA(At, 1, 1); PG8_STAGE(PG8_SB(1, 0), b3, voffB); PG8_STAGE(PG8_SB(1, 1), b3 + hstepB, voffB); PG8_STAGE(PG8_SA(1, 0), a3, voffA);
;             PG8_WAIT_V(8); PG8_WAIT_L(0); PG8_BAR; PG8_MMA(1, 0, At, B0); PG8_MMA(1, 1, At, B1); PG8_BAR; PG8_SCHED;
;         }
	s_cmp_eq_u32 s49, 15
	s_cselect_b32 s28, s50, s28
	s_cselect_b32 s29, s51, s29
	s_add_i32 m0, s2, 0x2000
	s_nop 0
	global_load_lds_dwordx4 v132, s[28:29]
	ds_read_b128 v[190:193], v155 offset:32768
	ds_read_b128 v[194:197], v155 offset:33792
	ds_read_b128 v[198:201], v155 offset:34816
	s_add_u32 s30, s28, 0x20000
	s_addc_u32 s31, s29, 0
	s_add_i32 m0, s2, 0x3000
	s_nop 0
	global_load_lds_dwordx4 v132, s[30:31]
	ds_read_b128 v[202:205], v155 offset:35840
	ds_read_b128 v[206:209], v155 offset:36864
	ds_read_b128 v[210:213], v155 offset:37888
	s_add_u32 s30, s28, 0x80000
	s_addc_u32 s31, s29, 0
	s_add_i32 m0, s2, 0x6000
	s_nop 0
	global_load_lds_dwordx4 v132, s[30:31]
	ds_read_b128 v[214:217], v155 offset:38912
	ds_read_b128 v[218:221], v155 offset:39936
	ds_read_b128 v[156:159], v153 offset:32768
	s_add_u32 s30, s28, 0xa0000
	s_addc_u32 s31, s29, 0
	s_add_i32 m0, s2, 0x7000
	s_nop 0
	global_load_lds_dwordx4 v132, s[30:31]
	ds_read_b128 v[160:163], v153 offset:33792
	ds_read_b128 v[164:167], v153 offset:34816
	ds_read_b128 v[168:171], v153 offset:35840
	s_add_u32 s34, s28, 0x80
	s_addc_u32 s35, s29, 0
	s_add_i32 m0, s2, 0x8000
	s_nop 0
	global_load_lds_dwordx4 v136, s[34:35]
	ds_read_b128 v[174:177], v153 offset:49152
	ds_read_b128 v[178:181], v153 offset:50176
	ds_read_b128 v[182:185], v153 offset:51200
	s_add_u32 s30, s34, 0x20000
	s_addc_u32 s31, s35, 0
	s_add_i32 m0, s2, 0x9000
	s_nop 0
	global_load_lds_dwordx4 v136, s[30:31]
	ds_read_b128 v[186:189], v153 offset:52224
	ds_read_b128 v[222:225], v155 offset:49152
	ds_read_b128 v[226:229], v155 offset:50176
	s_add_u32 s30, s34, 0x80000
	s_addc_u32 s31, s35, 0
	s_add_i32 m0, s2, 0xc000
	s_nop 0
	global_load_lds_dwordx4 v136, s[30:31]
	ds_read_b128 v[230:233], v155 offset:51200
	ds_read_b128 v[234:237], v155 offset:52224
	ds_read_b128 v[238:241], v155 offset:53248
	s_add_u32 s30, s34, 0xa0000
	s_addc_u32 s31, s35, 0
	s_add_i32 m0, s2, 0xd000
	s_nop 0
	global_load_lds_dwordx4 v136, s[30:31]
	ds_read_b128 v[242:245], v155 offset:54272
	ds_read_b128 v[246:249], v155 offset:55296
	ds_read_b128 v[250:253], v155 offset:56320
	s_add_u32 s28, s28, 0x80
	s_addc_u32 s29, s29, 0
	s_waitcnt vmcnt(8) lgkmcnt(0)
	s_barrier
	s_setprio 1
	v_mfma_f32_16x16x32_bf16 v[126:129], v[156:159], v[190:193], v[126:129]
	v_mfma_f32_16x16x32_bf16 v[126:129], v[160:163], v[194:197], v[126:129]
	v_mfma_f32_16x16x32_bf16 v[122:125], v[168:171], v[194:197], v[122:125]
	v_mfma_f32_16x16x32_bf16 v[122:125], v[164:167], v[190:193], v[122:125]
	v_mfma_f32_16x16x32_bf16 v[118:121], v[174:177], v[190:193], v[118:121]
	v_mfma_f32_16x16x32_bf16 v[118:121], v[178:181], v[194:197], v[118:121]
	v_mfma_f32_16x16x32_bf16 v[114:117], v[186:189], v[194:197], v[114:117]
	v_mfma_f32_16x16x32_bf16 v[114:117], v[182:185], v[190:193], v[114:117]
	v_mfma_f32_16x16x32_bf16 v[98:101], v[182:185], v[198:201], v[98:101]
	v_mfma_f32_16x16x32_bf16 v[98:101], v[186:189], v[202:205], v[98:101]
	v_mfma_f32_16x16x32_bf16 v[102:105], v[178:181], v[202:205], v[102:105]
	v_mfma_f32_16x16x32_bf16 v[102:105], v[174:177], v[198:201], v[102:105]
	v_mfma_f32_16x16x32_bf16 v[106:109], v[164:167], v[198:201], v[106:109]
	v_mfma_f32_16x16x32_bf16 v[106:109], v[168:171], v[202:205], v[106:109]
	v_mfma_f32_16x16x32_bf16 v[110:113], v[160:163], v[202:205], v[110:113]
	v_mfma_f32_16x16x32_bf16 v[110:113], v[156:159], v[198:201], v[110:113]
	v_mfma_f32_16x16x32_bf16 v[94:97], v[156:159], v[206:209], v[94:97]
	v_mfma_f32_16x16x32_bf16 v[94:97], v[160:163], v[210:213], v[94:97]
	v_mfma_f32_16x16x32_bf16 v[90:93], v[168:171], v[210:213], v[90:93]
	v_mfma_f32_16x16x32_bf16 v[90:93], v[164:167], v[206:209], v[90:93]
	v_mfma_f32_16x16x32_bf16 v[86:89], v[174:177], v[206:209], v[86:89]
	v_mfma_f32_16x16x32_bf16 v[86:89], v[178:181], v[210:213], v[86:89]
	v_mfma_f32_16x16x32_bf16 v[82:85], v[186:189], v[210:213], v[82:85]
	v_mfma_f32_16x16x32_bf16 v[82:85], v[182:185], v[206:209], v[82:85]
	v_mfma_f32_16x16x32_bf16 v[66:69], v[182:185], v[214:217], v[66:69]
	v_mfma_f32_16x16x32_bf16 v[66:69], v[186:189], v[218:221], v[66:69]
	v_mfma_f32_16x16x32_bf16 v[70:73], v[178:181], v[218:221], v[70:73]
	v_mfma_f32_16x16x32_bf16 v[70:73], v[174:177], v[214:217], v[70:73]
	v_mfma_f32_16x16x32_bf16 v[74:77], v[164:167], v[214:217], v[74:77]
	v_mfma_f32_16x16x32_bf16 v[74:77], v[168:171], v[218:221], v[74:77]
	v_mfma_f32_16x16x32_bf16 v[78:81], v[160:163], v[218:221], v[78:81]
	v_mfma_f32_16x16x32_bf16 v[78:81], v[156:159], v[214:217], v[78:81]
	v_mfma_f32_16x16x32_bf16 v[62:65], v[156:159], v[222:225], v[62:65]
	v_mfma_f32_16x16x32_bf16 v[62:65], v[160:163], v[226:229], v[62:65]
	v_mfma_f32_16x16x32_bf16 v[58:61], v[168:171], v[226:229], v[58:61]
	v_mfma_f32_16x16x32_bf16 v[58:61], v[164:167], v[222:225], v[58:61]
	v_mfma_f32_16x16x32_bf16 v[54:57], v[174:177], v[222:225], v[54:57]
	v_mfma_f32_16x16x32_bf16 v[54:57], v[178:181], v[226:229], v[54:57]
	v_mfma_f32_16x16x32_bf16 v[50:53], v[186:189], v[226:229], v[50:53]
	v_mfma_f32_16x16x32_bf16 v[50:53], v[182:185], v[222:225], v[50:53]
	v_mfma_f32_16x16x32_bf16 v[34:37], v[182:185], v[230:233], v[34:37]
	v_mfma_f32_16x16x32_bf16 v[34:37], v[186:189], v[234:237], v[34:37]
	v_mfma_f32_16x16x32_bf16 v[38:41], v[178:181], v[234:237], v[38:41]
	v_mfma_f32_16x16x32_bf16 v[38:41], v[174:177], v[230:233], v[38:41]
	v_mfma_f32_16x16x32_bf16 v[42:45], v[164:167], v[230:233], v[42:45]
	v_mfma_f32_16x16x32_bf16 v[42:45], v[168:171], v[234:237], v[42:45]
	v_mfma_f32_16x16x32_bf16 v[46:49], v[160:163], v[234:237], v[46:49]
	v_mfma_f32_16x16x32_bf16 v[46:49], v[156:159], v[230:233], v[46:49]
	v_mfma_f32_16x16x32_bf16 v[30:33], v[156:159], v[238:241], v[30:33]
	v_mfma_f32_16x16x32_bf16 v[30:33], v[160:163], v[242:245], v[30:33]
	v_mfma_f32_16x16x32_bf16 v[26:29], v[168:171], v[242:245], v[26:29]
	v_mfma_f32_16x16x32_bf16 v[26:29], v[164:167], v[238:241], v[26:29]
	v_mfma_f32_16x16x32_bf16 v[22:25], v[174:177], v[238:241], v[22:25]
	v_mfma_f32_16x16x32_bf16 v[22:25], v[178:181], v[242:245], v[22:25]
	v_mfma_f32_16x16x32_bf16 v[18:21], v[186:189], v[242:245], v[18:21]
	v_mfma_f32_16x16x32_bf16 v[18:21], v[182:185], v[238:241], v[18:21]
	v_mfma_f32_16x16x32_bf16 v[2:5], v[182:185], v[246:249], v[2:5]
	v_mfma_f32_16x16x32_bf16 v[2:5], v[186:189], v[250:253], v[2:5]
	v_mfma_f32_16x16x32_bf16 v[6:9], v[178:181], v[250:253], v[6:9]
	v_mfma_f32_16x16x32_bf16 v[6:9], v[174:177], v[246:249], v[6:9]
	v_mfma_f32_16x16x32_bf16 v[10:13], v[164:167], v[246:249], v[10:13]
	v_mfma_f32_16x16x32_bf16 v[10:13], v[168:171], v[250:253], v[10:13]
	v_mfma_f32_16x16x32_bf16 v[14:17], v[160:163], v[250:253], v[14:17]
	v_mfma_f32_16x16x32_bf16 v[14:17], v[156:159], v[246:249], v[14:17]
	s_setprio 0
	s_waitcnt vmcnt(0)
	s_barrier
	s_add_i32 s49, s49, 1
	s_cmp_lt_u32 s49, 16
	s_cbranch_scc1 .Lp8k_B_loop

; #define PG8_STAGE(bufoff, gbase, voff) do { _Pragma("unroll") for (int _i = 0; _i < 2; ++_i) \
;         __builtin_amdgcn_global_load_lds((const unsigned*)((const char*)(gbase) + (voff)[_i]), (PG8_LAS unsigned*)(lds + (bufoff) + ldsw + _i * 8192), 16, 0, 0); } while (0)
; #define PG8_LDA(dst, b, h) do { _Pragma("unroll") for (int m = 0; m < 4; ++m) _Pragma("unroll") for (int k = 0; k < 2; ++k) dst[m][k] = *(const PG8_LAS bf16x8*)(lds + PG8_SA(b, h) + aoff + m * 2048 + k * 1024); } while (0)
; #define PG8_LDB(dst, b, h) do { _Pragma("unroll") for (int n = 0; n < 2; ++n) _Pragma("unroll") for (int k = 0; k < 2; ++k) dst[n][k] = *(const PG8_LAS bf16x8*)(lds + PG8_SB(b, h) + boff + n * 2048 + k * 1024); } while (0)
; #define PG8_MMA(ai, bj, At, Bt) do { __builtin_amdgcn_s_setprio(1); _Pragma("unroll") for (int m = 0; m < 4; ++m) _Pragma("unroll") for (int n = 0; n < 2; ++n) _Pragma("unroll") for (int k = 0; k < 2; ++k) \
;         acc[ai][bj][m][n] = __builtin_amdgcn_mfma_f32_16x16x32_bf16(Bt[n][k], At[m][k], acc[ai][bj][m][n], 0, 0, 0); __builtin_amdgcn_s_setprio(0); } while (0)
; #define PG8_WAIT_V(n) asm volatile("s_waitcnt vmcnt(" #n ")" ::: "memory")
; #define PG8_WAIT_L(n) asm volatile("s_waitcnt lgkmcnt(" #n ")" ::: "memory")
; #define PG8_BAR __builtin_amdgcn_s_barrier()
; #define PG8_SCHED __builtin_amdgcn_sched_barrier(0)
; template <class Epi, class Sched, bool ALIGN_EPI>
; __device__ __forceinline__ void gemm_phase(PG8_LAS unsigned char* lds, const Gemm g, const Sched& S, const Epi& E) {
;     ...
;             PG8_LDB(B0, 0, 0); PG8_LDB(B1, 0, 1); PG8_SCHED; PG8_LDA(At, 0, 0); PG8_STAGE(PG8_SA(1, 1), a1 + hstepA, voffA);
;             PG8_WAIT_V(8); PG8_WAIT_L(0); PG8_BAR; PG8_MMA(0, 0, At, B0); PG8_MMA(0, 1, At, B1); PG8_BAR; PG8_SCHED;
;             PG8_LDA(At, 0, 1); PG8_STAGE(PG8_SB(0, 0), b2, voffB); PG8_STAGE(PG8_SB(0, 1), b2 + hstepB, voffB); PG8_STAGE(PG8_SA(0, 0), a2, voffA);
;             PG8_WAIT_V(8); PG8_WAIT_L(0); PG8_BAR; PG8_MMA(1, 0, At, B0); PG8_MMA(1, 1, At, B1); PG8_BAR; PG8_SCHED;
.Lp9k_A_loop:
	s_add_i32 m0, s60, 0x18000
	s_nop 0
	global_load_lds_dwordx4 v132, s[28:29]
	ds_read_b128 v[194:197], v157 offset:0
	ds_read_b128 v[198:201], v157 offset:1024
	ds_read_b128 v[202:205], v157 offset:2048
	s_add_i32 m0, s60, 0x1a000
	s_nop 0
	global_load_lds_dwordx4 v136, s[28:29]
	ds_read_b128 v[206:209], v157 offset:3072
	ds_read_b128 v[210:213], v157 offset:4096
	ds_read_b128 v[214:217], v157 offset:5120
	s_add_u32 s30, s28, 0x58000
	s_addc_u32 s31, s29, 0
	s_add_i32 m0, s60, 0x19000
	s_nop 0
	global_load_lds_dwordx4 v132, s[30:31]
	ds_read_b128 v[218:221], v157 offset:6144
	ds_read_b128 v[222:225], v157 offset:7168
	ds_read_b128 v[158:161], v155 offset:0
	s_add_i32 m0, s60, 0x1b000
	s_nop 0
	global_load_lds_dwordx4 v136, s[30:31]
	ds_read_b128 v[162:165], v155 offset:1024
	ds_read_b128 v[166:169], v155 offset:2048
	ds_read_b128 v[174:177], v155 offset:3072
	s_add_u32 s30, s28, 0x160000
	s_addc_u32 s31, s29, 0
	s_add_i32 m0, s60, 0x1c000
	s_nop 0
	global_load_lds_dwordx4 v132, s[30:31]
	ds_read_b128 v[178:181], v155 offset:16384
	ds_read_b128 v[182:185], v155 offset:17408
	ds_read_b128 v[186:189], v155 offset:18432
	s_add_i32 m0, s60, 0x1e000
	s_nop 0
	global_load_lds_dwordx4 v136, s[30:31]
	ds_read_b128 v[190:193], v155 offset:19456
	ds_read_b128 v[226:229], v157 offset:16384
	ds_read_b128 v[230:233], v157 offset:17408
	s_add_u32 s30, s28, 0x1b8000
	s_addc_u32 s31, s29, 0
	s_add_i32 m0, s60, 0x1d000
	s_nop 0
	global_load_lds_dwordx4 v132, s[30:31]
	ds_read_b128 v[234:237], v157 offset:18432
	ds_read_b128 v[238:241], v157 offset:19456
	ds_read_b128 v[242:245], v157 offset:20480
	s_add_i32 m0, s60, 0x1f000
	s_nop 0
	global_load_lds_dwordx4 v136, s[30:31]
	ds_read_b128 v[246:249], v157 offset:21504
	ds_read_b128 v[250:253], v157 offset:22528
	ds_read_b128 v[142:145], v157 offset:23552
	s_add_u32 s28, s28, 0x80
	s_addc_u32 s29, s29, 0
	s_waitcnt vmcnt(8) lgkmcnt(0)
	s_barrier
	s_setprio 1
	v_mfma_f32_16x16x32_bf16 v[126:129], v[158:161], v[194:197], v[126:129]
	v_mfma_f32_16x16x32_bf16 v[126:129], v[162:165], v[198:201], v[126:129]
	v_mfma_f32_16x16x32_bf16 v[122:125], v[174:177], v[198:201], v[122:125]
	v_mfma_f32_16x16x32_bf16 v[122:125], v[166:169], v[194:197], v[122:125]
	v_mfma_f32_16x16x32_bf16 v[114:117], v[178:181], v[194:197], v[114:117]
	v_mfma_f32_16x16x32_bf16 v[114:117], v[182:185], v[198:201], v[114:117]
	v_mfma_f32_16x16x32_bf16 v[106:109], v[190:193], v[198:201], v[106:109]
	v_mfma_f32_16x16x32_bf16 v[106:109], v[186:189], v[194:197], v[106:109]
	v_mfma_f32_16x16x32_bf16 v[90:93], v[186:189], v[202:205], v[90:93]
	v_mfma_f32_16x16x32_bf16 v[90:93], v[190:193], v[206:209], v[90:93]
	v_mfma_f32_16x16x32_bf16 v[98:101], v[182:185], v[206:209], v[98:101]
	v_mfma_f32_16x16x32_bf16 v[98:101], v[178:181], v[202:205], v[98:101]
	v_mfma_f32_16x16x32_bf16 v[110:113], v[166:169], v[202:205], v[110:113]
	v_mfma_f32_16x16x32_bf16 v[110:113], v[174:177], v[206:209], v[110:113]
	v_mfma_f32_16x16x32_bf16 v[118:121], v[162:165], v[206:209], v[118:121]
	v_mfma_f32_16x16x32_bf16 v[118:121], v[158:161], v[202:205], v[118:121]
	v_mfma_f32_16x16x32_bf16 v[102:105], v[158:161], v[210:213], v[102:105]
	v_mfma_f32_16x16x32_bf16 v[102:105], v[162:165], v[214:217], v[102:105]
	v_mfma_f32_16x16x32_bf16 v[94:97], v[174:177], v[214:217], v[94:97]
	v_mfma_f32_16x16x32_bf16 v[94:97], v[166:169], v[210:213], v[94:97]
	v_mfma_f32_16x16x32_bf16 v[82:85], v[178:181], v[210:213], v[82:85]
	v_mfma_f32_16x16x32_bf16 v[82:85], v[182:185], v[214:217], v[82:85]
	v_mfma_f32_16x16x32_bf16 v[74:77], v[190:193], v[214:217], v[74:77]
	v_mfma_f32_16x16x32_bf16 v[74:77], v[186:189], v[210:213], v[74:77]
	v_mfma_f32_16x16x32_bf16 v[66:69], v[186:189], v[218:221], v[66:69]
	v_mfma_f32_16x16x32_bf16 v[66:69], v[190:193], v[222:225], v[66:69]
	v_mfma_f32_16x16x32_bf16 v[70:73], v[182:185], v[222:225], v[70:73]
	v_mfma_f32_16x16x32_bf16 v[70:73], v[178:181], v[218:221], v[70:73]
	v_mfma_f32_16x16x32_bf16 v[78:81], v[166:169], v[218:221], v[78:81]
	v_mfma_f32_16x16x32_bf16 v[78:81], v[174:177], v[222:225], v[78:81]
	v_mfma_f32_16x16x32_bf16 v[86:89], v[162:165], v[222:225], v[86:89]
	v_mfma_f32_16x16x32_bf16 v[86:89], v[158:161], v[218:221], v[86:89]
	v_mfma_f32_16x16x32_bf16 v[62:65], v[158:161], v[226:229], v[62:65]
	v_mfma_f32_16x16x32_bf16 v[62:65], v[162:165], v[230:233], v[62:65]
	v_mfma_f32_16x16x32_bf16 v[58:61], v[174:177], v[230:233], v[58:61]
	v_mfma_f32_16x16x32_bf16 v[58:61], v[166:169], v[226:229], v[58:61]
	v_mfma_f32_16x16x32_bf16 v[50:53], v[178:181], v[226:229], v[50:53]
	v_mfma_f32_16x16x32_bf16 v[50:53], v[182:185], v[230:233], v[50:53]
	v_mfma_f32_16x16x32_bf16 v[42:45], v[190:193], v[230:233], v[42:45]
	v_mfma_f32_16x16x32_bf16 v[42:45], v[186:189], v[226:229], v[42:45]
	v_mfma_f32_16x16x32_bf16 v[26:29], v[186:189], v[234:237], v[26:29]
	v_mfma_f32_16x16x32_bf16 v[26:29], v[190:193], v[238:241], v[26:29]
	v_mfma_f32_16x16x32_bf16 v[34:37], v[182:185], v[238:241], v[34:37]
	v_mfma_f32_16x16x32_bf16 v[34:37], v[178:181], v[234:237], v[34:37]
	v_mfma_f32_16x16x32_bf16 v[46:49], v[166:169], v[234:237], v[46:49]
	v_mfma_f32_16x16x32_bf16 v[46:49], v[174:177], v[238:241], v[46:49]
	v_mfma_f32_16x16x32_bf16 v[54:57], v[162:165], v[238:241], v[54:57]
	v_mfma_f32_16x16x32_bf16 v[54:57], v[158:161], v[234:237], v[54:57]
	v_mfma_f32_16x16x32_bf16 v[38:41], v[158:161], v[242:245], v[38:41]
	v_mfma_f32_16x16x32_bf16 v[38:41], v[162:165], v[246:249], v[38:41]
	v_mfma_f32_16x16x32_bf16 v[30:33], v[174:177], v[246:249], v[30:33]
	v_mfma_f32_16x16x32_bf16 v[30:33], v[166:169], v[242:245], v[30:33]
	v_mfma_f32_16x16x32_bf16 v[18:21], v[178:181], v[242:245], v[18:21]
	v_mfma_f32_16x16x32_bf16 v[18:21], v[182:185], v[246:249], v[18:21]
	v_mfma_f32_16x16x32_bf16 v[10:13], v[190:193], v[246:249], v[10:13]
	v_mfma_f32_16x16x32_bf16 v[10:13], v[186:189], v[242:245], v[10:13]
	v_mfma_f32_16x16x32_bf16 v[2:5], v[186:189], v[250:253], v[2:5]
	v_mfma_f32_16x16x32_bf16 v[2:5], v[190:193], v[142:145], v[2:5]
	v_mfma_f32_16x16x32_bf16 v[6:9], v[182:185], v[142:145], v[6:9]
	v_mfma_f32_16x16x32_bf16 v[6:9], v[178:181], v[250:253], v[6:9]
	v_mfma_f32_16x16x32_bf16 v[14:17], v[166:169], v[250:253], v[14:17]
	v_mfma_f32_16x16x32_bf16 v[14:17], v[174:177], v[142:145], v[14:17]
	v_mfma_f32_16x16x32_bf16 v[22:25], v[162:165], v[142:145], v[22:25]
	v_mfma_f32_16x16x32_bf16 v[22:25], v[158:161], v[250:253], v[22:25]
	s_setprio 0
	s_waitcnt vmcnt(0)
	s_barrier
; #define PG8_STAGE(bufoff, gbase, voff) do { _Pragma("unroll") for (int _i = 0; _i < 2; ++_i) \
;         __builtin_amdgcn_global_load_lds((const unsigned*)((const char*)(gbase) + (voff)[_i]), (PG8_LAS unsigned*)(lds + (bufoff) + ldsw + _i * 8192), 16, 0, 0); } while (0)
; #define PG8_LDA(dst, b, h) do { _Pragma("unroll") for (int m = 0; m < 4; ++m) _Pragma("unroll") for (int k = 0; k < 2; ++k) dst[m][k] = *(const PG8_LAS bf16x8*)(lds + PG8_SA(b, h) + aoff + m * 2048 + k * 1024); } while (0)
; #define PG8_LDB(dst, b, h) do { _Pragma("unroll") for (int n = 0; n < 2; ++n) _Pragma("unroll") for (int k = 0; k < 2; ++k) dst[n][k] = *(const PG8_LAS bf16x8*)(lds + PG8_SB(b, h) + boff + n * 2048 + k * 1024); } while (0)
; #define PG8_MMA(ai, bj, At, Bt) do { __builtin_amdgcn_s_setprio(1); _Pragma("unroll") for (int m = 0; m < 4; ++m) _Pragma("unroll") for (int n = 0; n < 2; ++n) _Pragma("unroll") for (int k = 0; k < 2; ++k) \
;         acc[ai][bj][m][n] = __builtin_amdgcn_mfma_f32_16x16x32_bf16(Bt[n][k], At[m][k], acc[ai][bj][m][n], 0, 0, 0); __builtin_amdgcn_s_setprio(0); } while (0)
; #define PG8_WAIT_V(n) asm volatile("s_waitcnt vmcnt(" #n ")" ::: "memory")
; #define PG8_WAIT_L(n) asm volatile("s_waitcnt lgkmcnt(" #n ")" ::: "memory")
; #define PG8_BAR __builtin_amdgcn_s_barrier()
; #define PG8_SCHED __builtin_amdgcn_sched_barrier(0)
; template <class Epi, class Sched, bool ALIGN_EPI>
; __device__ __forceinline__ void gemm_phase(PG8_LAS unsigned char* lds, const Gemm g, const Sched& S, const Epi& E) {
;     ...
;             PG8_LDB(B0, 1, 0); PG8_LDB(B1, 1, 1); PG8_SCHED; PG8_LDA(At, 1, 0); PG8_STAGE(PG8_SA(0, 1), a2 + hstepA, voffA);
;             PG8_WAIT_V(8); PG8_WAIT_L(0); PG8_BAR; PG8_MMA(0, 0, At, B0); PG8_MMA(0, 1, At, B1); PG8_BAR; PG8_SCHED;
;             PG8_LDA(At, 1, 1); PG8_STAGE(PG8_SB(1, 0), b3, voffB); PG8_STAGE(PG8_SB(1, 1), b3 + hstepB, voffB); PG8_STAGE(PG8_SA(1, 0), a3, voffA);
;             PG8_WAIT_V(8); PG8_WAIT_L(0); PG8_BAR; PG8_MMA(1, 0, At, B0); PG8_MMA(1, 1, At, B1); PG8_BAR; PG8_SCHED;
;         }
	s_cmp_eq_u32 s57, 43
	s_cselect_b32 s28, s58, s28
	s_cselect_b32 s29, s59, s29
	s_add_i32 m0, s60, 0x10000
	s_nop 0
	global_load_lds_dwordx4 v132, s[28:29]
	ds_read_b128 v[194:197], v157 offset:32768
	ds_read_b128 v[198:201], v157 offset:33792
	ds_read_b128 v[202:205], v157 offset:34816
	s_add_i32 m0, s60, 0x12000
	s_nop 0
	global_load_lds_dwordx4 v136, s[28:29]
	ds_read_b128 v[206:209], v157 offset:35840
	ds_read_b128 v[210:213], v157 offset:36864
	ds_read_b128 v[214:217], v157 offset:37888
	s_add_u32 s30, s28, 0x58000
	s_addc_u32 s31, s29, 0
	s_add_i32 m0, s60, 0x11000
	s_nop 0
	global_load_lds_dwordx4 v132, s[30:31]
	ds_read_b128 v[218:221], v157 offset:38912
	ds_read_b128 v[222:225], v157 offset:39936
	ds_read_b128 v[158:161], v155 offset:32768
	s_add_i32 m0, s60, 0x13000
	s_nop 0
	global_load_lds_dwordx4 v136, s[30:31]
	ds_read_b128 v[162:165], v155 offset:33792
	ds_read_b128 v[166:169], v155 offset:34816
	ds_read_b128 v[174:177], v155 offset:35840
	s_add_u32 s30, s28, 0x160000
	s_addc_u32 s31, s29, 0
	s_add_i32 m0, s60, 0x14000
	s_nop 0
	global_load_lds_dwordx4 v132, s[30:31]
	ds_read_b128 v[178:181], v155 offset:49152
	ds_read_b128 v[182:185], v155 offset:50176
	ds_read_b128 v[186:189], v155 offset:51200
	s_add_i32 m0, s60, 0x16000
	s_nop 0
	global_load_lds_dwordx4 v136, s[30:31]
	ds_read_b128 v[190:193], v155 offset:52224
	ds_read_b128 v[226:229], v157 offset:49152
	ds_read_b128 v[230:233], v157 offset:50176
	s_add_u32 s30, s28, 0x1b8000
	s_addc_u32 s31, s29, 0
	s_add_i32 m0, s60, 0x15000
	s_nop 0
	global_load_lds_dwordx4 v132, s[30:31]
	ds_read_b128 v[234:237], v157 offset:51200
	ds_read_b128 v[238:241], v157 offset:52224
	ds_read_b128 v[242:245], v157 offset:53248
	s_add_i32 m0, s60, 0x17000
	s_nop 0
	global_load_lds_dwordx4 v136, s[30:31]
	ds_read_b128 v[246:249], v157 offset:54272
	ds_read_b128 v[250:253], v157 offset:55296
	ds_read_b128 v[142:145], v157 offset:56320
	s_add_u32 s28, s28, 0x80
	s_addc_u32 s29, s29, 0
	s_waitcnt vmcnt(8) lgkmcnt(0)
	s_barrier
	s_setprio 1
	v_mfma_f32_16x16x32_bf16 v[126:129], v[158:161], v[194:197], v[126:129]
	v_mfma_f32_16x16x32_bf16 v[126:129], v[162:165], v[198:201], v[126:129]
	v_mfma_f32_16x16x32_bf16 v[122:125], v[174:177], v[198:201], v[122:125]
	v_mfma_f32_16x16x32_bf16 v[122:125], v[166:169], v[194:197], v[122:125]
	v_mfma_f32_16x16x32_bf16 v[114:117], v[178:181], v[194:197], v[114:117]
	v_mfma_f32_16x16x32_bf16 v[114:117], v[182:185], v[198:201], v[114:117]
	v_mfma_f32_16x16x32_bf16 v[106:109], v[190:193], v[198:201], v[106:109]
	v_mfma_f32_16x16x32_bf16 v[106:109], v[186:189], v[194:197], v[106:109]
	v_mfma_f32_16x16x32_bf16 v[90:93], v[186:189], v[202:205], v[90:93]
	v_mfma_f32_16x16x32_bf16 v[90:93], v[190:193], v[206:209], v[90:93]
	v_mfma_f32_16x16x32_bf16 v[98:101], v[182:185], v[206:209], v[98:101]
	v_mfma_f32_16x16x32_bf16 v[98:101], v[178:181], v[202:205], v[98:101]
	v_mfma_f32_16x16x32_bf16 v[110:113], v[166:169], v[202:205], v[110:113]
	v_mfma_f32_16x16x32_bf16 v[110:113], v[174:177], v[206:209], v[110:113]
	v_mfma_f32_16x16x32_bf16 v[118:121], v[162:165], v[206:209], v[118:121]
	v_mfma_f32_16x16x32_bf16 v[118:121], v[158:161], v[202:205], v[118:121]
	v_mfma_f32_16x16x32_bf16 v[102:105], v[158:161], v[210:213], v[102:105]
	v_mfma_f32_16x16x32_bf16 v[102:105], v[162:165], v[214:217], v[102:105]
	v_mfma_f32_16x16x32_bf16 v[94:97], v[174:177], v[214:217], v[94:97]
	v_mfma_f32_16x16x32_bf16 v[94:97], v[166:169], v[210:213], v[94:97]
	v_mfma_f32_16x16x32_bf16 v[82:85], v[178:181], v[210:213], v[82:85]
	v_mfma_f32_16x16x32_bf16 v[82:85], v[182:185], v[214:217], v[82:85]
	v_mfma_f32_16x16x32_bf16 v[74:77], v[190:193], v[214:217], v[74:77]
	v_mfma_f32_16x16x32_bf16 v[74:77], v[186:189], v[210:213], v[74:77]
	v_mfma_f32_16x16x32_bf16 v[66:69], v[186:189], v[218:221], v[66:69]
	v_mfma_f32_16x16x32_bf16 v[66:69], v[190:193], v[222:225], v[66:69]
	v_mfma_f32_16x16x32_bf16 v[70:73], v[182:185], v[222:225], v[70:73]
	v_mfma_f32_16x16x32_bf16 v[70:73], v[178:181], v[218:221], v[70:73]
	v_mfma_f32_16x16x32_bf16 v[78:81], v[166:169], v[218:221], v[78:81]
	v_mfma_f32_16x16x32_bf16 v[78:81], v[174:177], v[222:225], v[78:81]
	v_mfma_f32_16x16x32_bf16 v[86:89], v[162:165], v[222:225], v[86:89]
	v_mfma_f32_16x16x32_bf16 v[86:89], v[158:161], v[218:221], v[86:89]
	v_mfma_f32_16x16x32_bf16 v[62:65], v[158:161], v[226:229], v[62:65]
	v_mfma_f32_16x16x32_bf16 v[62:65], v[162:165], v[230:233], v[62:65]
	v_mfma_f32_16x16x32_bf16 v[58:61], v[174:177], v[230:233], v[58:61]
	v_mfma_f32_16x16x32_bf16 v[58:61], v[166:169], v[226:229], v[58:61]
	v_mfma_f32_16x16x32_bf16 v[50:53], v[178:181], v[226:229], v[50:53]
	v_mfma_f32_16x16x32_bf16 v[50:53], v[182:185], v[230:233], v[50:53]
	v_mfma_f32_16x16x32_bf16 v[42:45], v[190:193], v[230:233], v[42:45]
	v_mfma_f32_16x16x32_bf16 v[42:45], v[186:189], v[226:229], v[42:45]
	v_mfma_f32_16x16x32_bf16 v[26:29], v[186:189], v[234:237], v[26:29]
	v_mfma_f32_16x16x32_bf16 v[26:29], v[190:193], v[238:241], v[26:29]
	v_mfma_f32_16x16x32_bf16 v[34:37], v[182:185], v[238:241], v[34:37]
	v_mfma_f32_16x16x32_bf16 v[34:37], v[178:181], v[234:237], v[34:37]
	v_mfma_f32_16x16x32_bf16 v[46:49], v[166:169], v[234:237], v[46:49]
	v_mfma_f32_16x16x32_bf16 v[46:49], v[174:177], v[238:241], v[46:49]
	v_mfma_f32_16x16x32_bf16 v[54:57], v[162:165], v[238:241], v[54:57]
	v_mfma_f32_16x16x32_bf16 v[54:57], v[158:161], v[234:237], v[54:57]
	v_mfma_f32_16x16x32_bf16 v[38:41], v[158:161], v[242:245], v[38:41]
	v_mfma_f32_16x16x32_bf16 v[38:41], v[162:165], v[246:249], v[38:41]
	v_mfma_f32_16x16x32_bf16 v[30:33], v[174:177], v[246:249], v[30:33]
	v_mfma_f32_16x16x32_bf16 v[30:33], v[166:169], v[242:245], v[30:33]
	v_mfma_f32_16x16x32_bf16 v[18:21], v[178:181], v[242:245], v[18:21]
	v_mfma_f32_16x16x32_bf16 v[18:21], v[182:185], v[246:249], v[18:21]
	v_mfma_f32_16x16x32_bf16 v[10:13], v[190:193], v[246:249], v[10:13]
	v_mfma_f32_16x16x32_bf16 v[10:13], v[186:189], v[242:245], v[10:13]
	v_mfma_f32_16x16x32_bf16 v[2:5], v[186:189], v[250:253], v[2:5]
	v_mfma_f32_16x16x32_bf16 v[2:5], v[190:193], v[142:145], v[2:5]
	v_mfma_f32_16x16x32_bf16 v[6:9], v[182:185], v[142:145], v[6:9]
	v_mfma_f32_16x16x32_bf16 v[6:9], v[178:181], v[250:253], v[6:9]
	v_mfma_f32_16x16x32_bf16 v[14:17], v[166:169], v[250:253], v[14:17]
	v_mfma_f32_16x16x32_bf16 v[14:17], v[174:177], v[142:145], v[14:17]
	v_mfma_f32_16x16x32_bf16 v[22:25], v[162:165], v[142:145], v[22:25]
	v_mfma_f32_16x16x32_bf16 v[22:25], v[158:161], v[250:253], v[22:25]
	s_setprio 0
	s_waitcnt vmcnt(0)
	s_barrier
	s_add_i32 s57, s57, 1
	s_cmp_lt_u32 s57, 44
	s_cbranch_scc1 .Lp9k_A_loop
	s_branch .Lp9k_done

; #define PG8_STAGE(bufoff, gbase, voff) do { _Pragma("unroll") for (int _i = 0; _i < 2; ++_i) \
;         __builtin_amdgcn_global_load_lds((const unsigned*)((const char*)(gbase) + (voff)[_i]), (PG8_LAS unsigned*)(lds + (bufoff) + ldsw + _i * 8192), 16, 0, 0); } while (0)
; #define PG8_LDA(dst, b, h) do { _Pragma("unroll") for (int m = 0; m < 4; ++m) _Pragma("unroll") for (int k = 0; k < 2; ++k) dst[m][k] = *(const PG8_LAS bf16x8*)(lds + PG8_SA(b, h) + aoff + m * 2048 + k * 1024); } while (0)
; #define PG8_LDB(dst, b, h) do { _Pragma("unroll") for (int n = 0; n < 2; ++n) _Pragma("unroll") for (int k = 0; k < 2; ++k) dst[n][k] = *(const PG8_LAS bf16x8*)(lds + PG8_SB(b, h) + boff + n * 2048 + k * 1024); } while (0)
; #define PG8_MMA(ai, bj, At, Bt) do { __builtin_amdgcn_s_setprio(1); _Pragma("unroll") for (int m = 0; m < 4; ++m) _Pragma("unroll") for (int n = 0; n < 2; ++n) _Pragma("unroll") for (int k = 0; k < 2; ++k) \
;         acc[ai][bj][m][n] = __builtin_amdgcn_mfma_f32_16x16x32_bf16(Bt[n][k], At[m][k], acc[ai][bj][m][n], 0, 0, 0); __builtin_amdgcn_s_setprio(0); } while (0)
; #define PG8_WAIT_V(n) asm volatile("s_waitcnt vmcnt(" #n ")" ::: "memory")
; #define PG8_WAIT_L(n) asm volatile("s_waitcnt lgkmcnt(" #n ")" ::: "memory")
; #define PG8_BAR __builtin_amdgcn_s_barrier()
; #define PG8_SCHED __builtin_amdgcn_sched_barrier(0)
; template <class Epi, class Sched, bool ALIGN_EPI>
; __device__ __forceinline__ void gemm_phase(PG8_LAS unsigned char* lds, const Gemm g, const Sched& S, const Epi& E) {
;     ...
;             PG8_LDB(B0, 0, 0); PG8_LDB(B1, 0, 1); PG8_SCHED; PG8_LDA(At, 0, 0); PG8_STAGE(PG8_SA(1, 1), a1 + hstepA, voffA);
;             PG8_WAIT_V(8); PG8_WAIT_L(0); PG8_BAR; PG8_MMA(0, 0, At, B0); PG8_MMA(0, 1, At, B1); PG8_BAR; PG8_SCHED;
;             PG8_LDA(At, 0, 1); PG8_STAGE(PG8_SB(0, 0), b2, voffB); PG8_STAGE(PG8_SB(0, 1), b2 + hstepB, voffB); PG8_STAGE(PG8_SA(0, 0), a2, voffA);
;             PG8_WAIT_V(8); PG8_WAIT_L(0); PG8_BAR; PG8_MMA(1, 0, At, B0); PG8_MMA(1, 1, At, B1); PG8_BAR; PG8_SCHED;
.Lp9k_B_loop:
	s_add_i32 m0, s60, 0xa000
	s_nop 0
	global_load_lds_dwordx4 v134, s[28:29]
	ds_read_b128 v[194:197], v157 offset:0
	ds_read_b128 v[198:201], v157 offset:1024
	ds_read_b128 v[202:205], v157 offset:2048
	s_add_u32 s30, s28, 0x58000
	s_addc_u32 s31, s29, 0
	s_add_i32 m0, s60, 0xb000
	s_nop 0
	global_load_lds_dwordx4 v134, s[30:31]
	ds_read_b128 v[206:209], v157 offset:3072
	ds_read_b128 v[210:213], v157 offset:4096
	ds_read_b128 v[214:217], v157 offset:5120
	s_add_u32 s30, s28, 0x160000
	s_addc_u32 s31, s29, 0
	s_add_i32 m0, s60, 0xe000
	s_nop 0
	global_load_lds_dwordx4 v134, s[30:31]
	ds_read_b128 v[218:221], v157 offset:6144
	ds_read_b128 v[222:225], v157 offset:7168
	ds_read_b128 v[158:161], v155 offset:0
	s_add_u32 s30, s28, 0x1b8000
	s_addc_u32 s31, s29, 0
	s_add_i32 m0, s60, 0xf000
	s_nop 0
	global_load_lds_dwordx4 v134, s[30:31]
	ds_read_b128 v[162:165], v155 offset:1024
	ds_read_b128 v[166:169], v155 offset:2048
	ds_read_b128 v[174:177], v155 offset:3072
	s_add_u32 s34, s28, 0x80
	s_addc_u32 s35, s29, 0
	s_cmp_eq_u32 s57, 43
	s_cselect_b32 s34, s58, s34
	s_cselect_b32 s35, s59, s35
	s_add_i32 m0, s60, 0x0
	s_nop 0
	global_load_lds_dwordx4 v130, s[34:35]
	ds_read_b128 v[178:181], v155 offset:16384
	ds_read_b128 v[182:185], v155 offset:17408
	ds_read_b128 v[186:189], v155 offset:18432
	s_add_u32 s30, s34, 0x58000
	s_addc_u32 s31, s35, 0
	s_add_i32 m0, s60, 0x1000
	s_nop 0
	global_load_lds_dwordx4 v130, s[30:31]
	ds_read_b128 v[190:193], v155 offset:19456
	ds_read_b128 v[226:229], v157 offset:16384
	ds_read_b128 v[230:233], v157 offset:17408
	s_add_u32 s30, s34, 0x160000
	s_addc_u32 s31, s35, 0
	s_add_i32 m0, s60, 0x4000
	s_nop 0
	global_load_lds_dwordx4 v130, s[30:31]
	ds_read_b128 v[234:237], v157 offset:18432
	ds_read_b128 v[238:241], v157 offset:19456
	ds_read_b128 v[242:245], v157 offset:20480
	s_add_u32 s30, s34, 0x1b8000
	s_addc_u32 s31, s35, 0
	s_add_i32 m0, s60, 0x5000
	s_nop 0
	global_load_lds_dwordx4 v130, s[30:31]
	ds_read_b128 v[246:249], v157 offset:21504
	ds_read_b128 v[250:253], v157 offset:22528
	ds_read_b128 v[142:145], v157 offset:23552
	s_add_u32 s28, s28, 0x80
	s_addc_u32 s29, s29, 0
	s_waitcnt vmcnt(8) lgkmcnt(0)
	s_barrier
	s_setprio 1
	v_mfma_f32_16x16x32_bf16 v[126:129], v[158:161], v[194:197], v[126:129]
	v_mfma_f32_16x16x32_bf16 v[126:129], v[162:165], v[198:201], v[126:129]
	v_mfma_f32_16x16x32_bf16 v[122:125], v[174:177], v[198:201], v[122:125]
	v_mfma_f32_16x16x32_bf16 v[122:125], v[166:169], v[194:197], v[122:125]
	v_mfma_f32_16x16x32_bf16 v[114:117], v[178:181], v[194:197], v[114:117]
	v_mfma_f32_16x16x32_bf16 v[114:117], v[182:185], v[198:201], v[114:117]
	v_mfma_f32_16x16x32_bf16 v[106:109], v[190:193], v[198:201], v[106:109]
	v_mfma_f32_16x16x32_bf16 v[106:109], v[186:189], v[194:197], v[106:109]
	v_mfma_f32_16x16x32_bf16 v[90:93], v[186:189], v[202:205], v[90:93]
	v_mfma_f32_16x16x32_bf16 v[90:93], v[190:193], v[206:209], v[90:93]
	v_mfma_f32_16x16x32_bf16 v[98:101], v[182:185], v[206:209], v[98:101]
	v_mfma_f32_16x16x32_bf16 v[98:101], v[178:181], v[202:205], v[98:101]
	v_mfma_f32_16x16x32_bf16 v[110:113], v[166:169], v[202:205], v[110:113]
	v_mfma_f32_16x16x32_bf16 v[110:113], v[174:177], v[206:209], v[110:113]
	v_mfma_f32_16x16x32_bf16 v[118:121], v[162:165], v[206:209], v[118:121]
	v_mfma_f32_16x16x32_bf16 v[118:121], v[158:161], v[202:205], v[118:121]
	v_mfma_f32_16x16x32_bf16 v[102:105], v[158:161], v[210:213], v[102:105]
	v_mfma_f32_16x16x32_bf16 v[102:105], v[162:165], v[214:217], v[102:105]
	v_mfma_f32_16x16x32_bf16 v[94:97], v[174:177], v[214:217], v[94:97]
	v_mfma_f32_16x16x32_bf16 v[94:97], v[166:169], v[210:213], v[94:97]
	v_mfma_f32_16x16x32_bf16 v[82:85], v[178:181], v[210:213], v[82:85]
	v_mfma_f32_16x16x32_bf16 v[82:85], v[182:185], v[214:217], v[82:85]
	v_mfma_f32_16x16x32_bf16 v[74:77], v[190:193], v[214:217], v[74:77]
	v_mfma_f32_16x16x32_bf16 v[74:77], v[186:189], v[210:213], v[74:77]
	v_mfma_f32_16x16x32_bf16 v[66:69], v[186:189], v[218:221], v[66:69]
	v_mfma_f32_16x16x32_bf16 v[66:69], v[190:193], v[222:225], v[66:69]
	v_mfma_f32_16x16x32_bf16 v[70:73], v[182:185], v[222:225], v[70:73]
	v_mfma_f32_16x16x32_bf16 v[70:73], v[178:181], v[218:221], v[70:73]
	v_mfma_f32_16x16x32_bf16 v[78:81], v[166:169], v[218:221], v[78:81]
	v_mfma_f32_16x16x32_bf16 v[78:81], v[174:177], v[222:225], v[78:81]
	v_mfma_f32_16x16x32_bf16 v[86:89], v[162:165], v[222:225], v[86:89]
	v_mfma_f32_16x16x32_bf16 v[86:89], v[158:161], v[218:221], v[86:89]
	v_mfma_f32_16x16x32_bf16 v[62:65], v[158:161], v[226:229], v[62:65]
	v_mfma_f32_16x16x32_bf16 v[62:65], v[162:165], v[230:233], v[62:65]
	v_mfma_f32_16x16x32_bf16 v[58:61], v[174:177], v[230:233], v[58:61]
	v_mfma_f32_16x16x32_bf16 v[58:61], v[166:169], v[226:229], v[58:61]
	v_mfma_f32_16x16x32_bf16 v[50:53], v[178:181], v[226:229], v[50:53]
	v_mfma_f32_16x16x32_bf16 v[50:53], v[182:185], v[230:233], v[50:53]
	v_mfma_f32_16x16x32_bf16 v[42:45], v[190:193], v[230:233], v[42:45]
	v_mfma_f32_16x16x32_bf16 v[42:45], v[186:189], v[226:229], v[42:45]
	v_mfma_f32_16x16x32_bf16 v[26:29], v[186:189], v[234:237], v[26:29]
	v_mfma_f32_16x16x32_bf16 v[26:29], v[190:193], v[238:241], v[26:29]
	v_mfma_f32_16x16x32_bf16 v[34:37], v[182:185], v[238:241], v[34:37]
	v_mfma_f32_16x16x32_bf16 v[34:37], v[178:181], v[234:237], v[34:37]
	v_mfma_f32_16x16x32_bf16 v[46:49], v[166:169], v[234:237], v[46:49]
	v_mfma_f32_16x16x32_bf16 v[46:49], v[174:177], v[238:241], v[46:49]
	v_mfma_f32_16x16x32_bf16 v[54:57], v[162:165], v[238:241], v[54:57]
	v_mfma_f32_16x16x32_bf16 v[54:57], v[158:161], v[234:237], v[54:57]
	v_mfma_f32_16x16x32_bf16 v[38:41], v[158:161], v[242:245], v[38:41]
	v_mfma_f32_16x16x32_bf16 v[38:41], v[162:165], v[246:249], v[38:41]
	v_mfma_f32_16x16x32_bf16 v[30:33], v[174:177], v[246:249], v[30:33]
	v_mfma_f32_16x16x32_bf16 v[30:33], v[166:169], v[242:245], v[30:33]
	v_mfma_f32_16x16x32_bf16 v[18:21], v[178:181], v[242:245], v[18:21]
	v_mfma_f32_16x16x32_bf16 v[18:21], v[182:185], v[246:249], v[18:21]
	v_mfma_f32_16x16x32_bf16 v[10:13], v[190:193], v[246:249], v[10:13]
	v_mfma_f32_16x16x32_bf16 v[10:13], v[186:189], v[242:245], v[10:13]
	v_mfma_f32_16x16x32_bf16 v[2:5], v[186:189], v[250:253], v[2:5]
	v_mfma_f32_16x16x32_bf16 v[2:5], v[190:193], v[142:145], v[2:5]
	v_mfma_f32_16x16x32_bf16 v[6:9], v[182:185], v[142:145], v[6:9]
	v_mfma_f32_16x16x32_bf16 v[6:9], v[178:181], v[250:253], v[6:9]
	v_mfma_f32_16x16x32_bf16 v[14:17], v[166:169], v[250:253], v[14:17]
	v_mfma_f32_16x16x32_bf16 v[14:17], v[174:177], v[142:145], v[14:17]
	v_mfma_f32_16x16x32_bf16 v[22:25], v[162:165], v[142:145], v[22:25]
	v_mfma_f32_16x16x32_bf16 v[22:25], v[158:161], v[250:253], v[22:25]
	s_setprio 0
	s_waitcnt vmcnt(0)
	s_barrier
; #define PG8_STAGE(bufoff, gbase, voff) do { _Pragma("unroll") for (int _i = 0; _i < 2; ++_i) \
;         __builtin_amdgcn_global_load_lds((const unsigned*)((const char*)(gbase) + (voff)[_i]), (PG8_LAS unsigned*)(lds + (bufoff) + ldsw + _i * 8192), 16, 0, 0); } while (0)
; #define PG8_LDA(dst, b, h) do { _Pragma("unroll") for (int m = 0; m < 4; ++m) _Pragma("unroll") for (int k = 0; k < 2; ++k) dst[m][k] = *(const PG8_LAS bf16x8*)(lds + PG8_SA(b, h) + aoff + m * 2048 + k * 1024); } while (0)
; #define PG8_LDB(dst, b, h) do { _Pragma("unroll") for (int n = 0; n < 2; ++n) _Pragma("unroll") for (int k = 0; k < 2; ++k) dst[n][k] = *(const PG8_LAS bf16x8*)(lds + PG8_SB(b, h) + boff + n * 2048 + k * 1024); } while (0)
; #define PG8_MMA(ai, bj, At, Bt) do { __builtin_amdgcn_s_setprio(1); _Pragma("unroll") for (int m = 0; m < 4; ++m) _Pragma("unroll") for (int n = 0; n < 2; ++n) _Pragma("unroll") for (int k = 0; k < 2; ++k) \
;         acc[ai][bj][m][n] = __builtin_amdgcn_mfma_f32_16x16x32_bf16(Bt[n][k], At[m][k], acc[ai][bj][m][n], 0, 0, 0); __builtin_amdgcn_s_setprio(0); } while (0)
; #define PG8_WAIT_V(n) asm volatile("s_waitcnt vmcnt(" #n ")" ::: "memory")
; #define PG8_WAIT_L(n) asm volatile("s_waitcnt lgkmcnt(" #n ")" ::: "memory")
; #define PG8_BAR __builtin_amdgcn_s_barrier()
; #define PG8_SCHED __builtin_amdgcn_sched_barrier(0)
; template <class Epi, class Sched, bool ALIGN_EPI>
; __device__ __forceinline__ void gemm_phase(PG8_LAS unsigned char* lds, const Gemm g, const Sched& S, const Epi& E) {
;     ...
;             PG8_LDB(B0, 1, 0); PG8_LDB(B1, 1, 1); PG8_SCHED; PG8_LDA(At, 1, 0); PG8_STAGE(PG8_SA(0, 1), a2 + hstepA, voffA);
;             PG8_WAIT_V(8); PG8_WAIT_L(0); PG8_BAR; PG8_MMA(0, 0, At, B0); PG8_MMA(0, 1, At, B1); PG8_BAR; PG8_SCHED;
;             PG8_LDA(At, 1, 1); PG8_STAGE(PG8_SB(1, 0), b3, voffB); PG8_STAGE(PG8_SB(1, 1), b3 + hstepB, voffB); PG8_STAGE(PG8_SA(1, 0), a3, voffA);
;             PG8_WAIT_V(8); PG8_WAIT_L(0); PG8_BAR; PG8_MMA(1, 0, At, B0); PG8_MMA(1, 1, At, B1); PG8_BAR; PG8_SCHED;
;         }
	s_cmp_eq_u32 s57, 43
	s_cselect_b32 s28, s58, s28
	s_cselect_b32 s29, s59, s29
	s_add_i32 m0, s60, 0x2000
	s_nop 0
	global_load_lds_dwordx4 v134, s[28:29]
	ds_read_b128 v[194:197], v157 offset:32768
	ds_read_b128 v[198:201], v157 offset:33792
	ds_read_b128 v[202:205], v157 offset:34816
	s_add_u32 s30, s28, 0x58000
	s_addc_u32 s31, s29, 0
	s_add_i32 m0, s60, 0x3000
	s_nop 0
	global_load_lds_dwordx4 v134, s[30:31]
	ds_read_b128 v[206:209], v157 offset:35840
	ds_read_b128 v[210:213], v157 offset:36864
	ds_read_b128 v[214:217], v157 offset:37888
	s_add_u32 s30, s28, 0x160000
	s_addc_u32 s31, s29, 0
	s_add_i32 m0, s60, 0x6000
	s_nop 0
	global_load_lds_dwordx4 v134, s[30:31]
	ds_read_b128 v[218:221], v157 offset:38912
	ds_read_b128 v[222:225], v157 offset:39936
	ds_read_b128 v[158:161], v155 offset:32768
	s_add_u32 s30, s28, 0x1b8000
	s_addc_u32 s31, s29, 0
	s_add_i32 m0, s60, 0x7000
	s_nop 0
	global_load_lds_dwordx4 v134, s[30:31]
	ds_read_b128 v[162:165], v155 offset:33792
	ds_read_b128 v[166:169], v155 offset:34816
	ds_read_b128 v[174:177], v155 offset:35840
	s_add_u32 s34, s28, 0x80
	s_addc_u32 s35, s29, 0
	s_add_i32 m0, s60, 0x8000
	s_nop 0
	global_load_lds_dwordx4 v130, s[34:35]
	ds_read_b128 v[178:181], v155 offset:49152
	ds_read_b128 v[182:185], v155 offset:50176
	ds_read_b128 v[186:189], v155 offset:51200
	s_add_u32 s30, s34, 0x58000
	s_addc_u32 s31, s35, 0
	s_add_i32 m0, s60, 0x9000
	s_nop 0
	global_load_lds_dwordx4 v130, s[30:31]
	ds_read_b128 v[190:193], v155 offset:52224
	ds_read_b128 v[226:229], v157 offset:49152
	ds_read_b128 v[230:233], v157 offset:50176
	s_add_u32 s30, s34, 0x160000
	s_addc_u32 s31, s35, 0
	s_add_i32 m0, s60, 0xc000
	s_nop 0
	global_load_lds_dwordx4 v130, s[30:31]
	ds_read_b128 v[234:237], v157 offset:51200
	ds_read_b128 v[238:241], v157 offset:52224
	ds_read_b128 v[242:245], v157 offset:53248
	s_add_u32 s30, s34, 0x1b8000
	s_addc_u32 s31, s35, 0
	s_add_i32 m0, s60, 0xd000
	s_nop 0
	global_load_lds_dwordx4 v130, s[30:31]
	ds_read_b128 v[246:249], v157 offset:54272
	ds_read_b128 v[250:253], v157 offset:55296
	ds_read_b128 v[142:145], v157 offset:56320
	s_add_u32 s28, s28, 0x80
	s_addc_u32 s29, s29, 0
	s_waitcnt vmcnt(8) lgkmcnt(0)
	s_barrier
	s_setprio 1
	v_mfma_f32_16x16x32_bf16 v[126:129], v[158:161], v[194:197], v[126:129]
	v_mfma_f32_16x16x32_bf16 v[126:129], v[162:165], v[198:201], v[126:129]
	v_mfma_f32_16x16x32_bf16 v[122:125], v[174:177], v[198:201], v[122:125]
	v_mfma_f32_16x16x32_bf16 v[122:125], v[166:169], v[194:197], v[122:125]
	v_mfma_f32_16x16x32_bf16 v[114:117], v[178:181], v[194:197], v[114:117]
	v_mfma_f32_16x16x32_bf16 v[114:117], v[182:185], v[198:201], v[114:117]
	v_mfma_f32_16x16x32_bf16 v[106:109], v[190:193], v[198:201], v[106:109]
	v_mfma_f32_16x16x32_bf16 v[106:109], v[186:189], v[194:197], v[106:109]
	v_mfma_f32_16x16x32_bf16 v[90:93], v[186:189], v[202:205], v[90:93]
	v_mfma_f32_16x16x32_bf16 v[90:93], v[190:193], v[206:209], v[90:93]
	v_mfma_f32_16x16x32_bf16 v[98:101], v[182:185], v[206:209], v[98:101]
	v_mfma_f32_16x16x32_bf16 v[98:101], v[178:181], v[202:205], v[98:101]
	v_mfma_f32_16x16x32_bf16 v[110:113], v[166:169], v[202:205], v[110:113]
	v_mfma_f32_16x16x32_bf16 v[110:113], v[174:177], v[206:209], v[110:113]
	v_mfma_f32_16x16x32_bf16 v[118:121], v[162:165], v[206:209], v[118:121]
	v_mfma_f32_16x16x32_bf16 v[118:121], v[158:161], v[202:205], v[118:121]
	v_mfma_f32_16x16x32_bf16 v[102:105], v[158:161], v[210:213], v[102:105]
	v_mfma_f32_16x16x32_bf16 v[102:105], v[162:165], v[214:217], v[102:105]
	v_mfma_f32_16x16x32_bf16 v[94:97], v[174:177], v[214:217], v[94:97]
	v_mfma_f32_16x16x32_bf16 v[94:97], v[166:169], v[210:213], v[94:97]
	v_mfma_f32_16x16x32_bf16 v[82:85], v[178:181], v[210:213], v[82:85]
	v_mfma_f32_16x16x32_bf16 v[82:85], v[182:185], v[214:217], v[82:85]
	v_mfma_f32_16x16x32_bf16 v[74:77], v[190:193], v[214:217], v[74:77]
	v_mfma_f32_16x16x32_bf16 v[74:77], v[186:189], v[210:213], v[74:77]
	v_mfma_f32_16x16x32_bf16 v[66:69], v[186:189], v[218:221], v[66:69]
	v_mfma_f32_16x16x32_bf16 v[66:69], v[190:193], v[222:225], v[66:69]
	v_mfma_f32_16x16x32_bf16 v[70:73], v[182:185], v[222:225], v[70:73]
	v_mfma_f32_16x16x32_bf16 v[70:73], v[178:181], v[218:221], v[70:73]
	v_mfma_f32_16x16x32_bf16 v[78:81], v[166:169], v[218:221], v[78:81]
	v_mfma_f32_16x16x32_bf16 v[78:81], v[174:177], v[222:225], v[78:81]
	v_mfma_f32_16x16x32_bf16 v[86:89], v[162:165], v[222:225], v[86:89]
	v_mfma_f32_16x16x32_bf16 v[86:89], v[158:161], v[218:221], v[86:89]
	v_mfma_f32_16x16x32_bf16 v[62:65], v[158:161], v[226:229], v[62:65]
	v_mfma_f32_16x16x32_bf16 v[62:65], v[162:165], v[230:233], v[62:65]
	v_mfma_f32_16x16x32_bf16 v[58:61], v[174:177], v[230:233], v[58:61]
	v_mfma_f32_16x16x32_bf16 v[58:61], v[166:169], v[226:229], v[58:61]
	v_mfma_f32_16x16x32_bf16 v[50:53], v[178:181], v[226:229], v[50:53]
	v_mfma_f32_16x16x32_bf16 v[50:53], v[182:185], v[230:233], v[50:53]
	v_mfma_f32_16x16x32_bf16 v[42:45], v[190:193], v[230:233], v[42:45]
	v_mfma_f32_16x16x32_bf16 v[42:45], v[186:189], v[226:229], v[42:45]
	v_mfma_f32_16x16x32_bf16 v[26:29], v[186:189], v[234:237], v[26:29]
	v_mfma_f32_16x16x32_bf16 v[26:29], v[190:193], v[238:241], v[26:29]
	v_mfma_f32_16x16x32_bf16 v[34:37], v[182:185], v[238:241], v[34:37]
	v_mfma_f32_16x16x32_bf16 v[34:37], v[178:181], v[234:237], v[34:37]
	v_mfma_f32_16x16x32_bf16 v[46:49], v[166:169], v[234:237], v[46:49]
	v_mfma_f32_16x16x32_bf16 v[46:49], v[174:177], v[238:241], v[46:49]
	v_mfma_f32_16x16x32_bf16 v[54:57], v[162:165], v[238:241], v[54:57]
	v_mfma_f32_16x16x32_bf16 v[54:57], v[158:161], v[234:237], v[54:57]
	v_mfma_f32_16x16x32_bf16 v[38:41], v[158:161], v[242:245], v[38:41]
	v_mfma_f32_16x16x32_bf16 v[38:41], v[162:165], v[246:249], v[38:41]
	v_mfma_f32_16x16x32_bf16 v[30:33], v[174:177], v[246:249], v[30:33]
	v_mfma_f32_16x16x32_bf16 v[30:33], v[166:169], v[242:245], v[30:33]
	v_mfma_f32_16x16x32_bf16 v[18:21], v[178:181], v[242:245], v[18:21]
	v_mfma_f32_16x16x32_bf16 v[18:21], v[182:185], v[246:249], v[18:21]
	v_mfma_f32_16x16x32_bf16 v[10:13], v[190:193], v[246:249], v[10:13]
	v_mfma_f32_16x16x32_bf16 v[10:13], v[186:189], v[242:245], v[10:13]
	v_mfma_f32_16x16x32_bf16 v[2:5], v[186:189], v[250:253], v[2:5]
	v_mfma_f32_16x16x32_bf16 v[2:5], v[190:193], v[142:145], v[2:5]
	v_mfma_f32_16x16x32_bf16 v[6:9], v[182:185], v[142:145], v[6:9]
	v_mfma_f32_16x16x32_bf16 v[6:9], v[178:181], v[250:253], v[6:9]
	v_mfma_f32_16x16x32_bf16 v[14:17], v[166:169], v[250:253], v[14:17]
	v_mfma_f32_16x16x32_bf16 v[14:17], v[174:177], v[142:145], v[14:17]
	v_mfma_f32_16x16x32_bf16 v[22:25], v[162:165], v[142:145], v[22:25]
	v_mfma_f32_16x16x32_bf16 v[22:25], v[158:161], v[250:253], v[22:25]
	s_setprio 0
	s_waitcnt vmcnt(0)
	s_barrier
	s_add_i32 s57, s57, 1
	s_cmp_lt_u32 s57, 44
	s_cbranch_scc1 .Lp9k_B_loop
